# also de-serialised layer-0 W_out residual epilogue (input pointers selected once per block) and split-K tail epilogues (16 gate loads hoisted, atomics streamed)
# speedup vs baseline: 1.1445x; 1.0108x over previous
.LBB0_291:
	v_readlane_b32 s8, v219, 0
	v_readlane_b32 s9, v219, 1
	s_and_b64 vcc, exec, s[8:9]
	s_cbranch_vccz .LBB0_301
	v_readlane_b32 s9, v219, 2
	v_mov_b32_e32 v97, v140
	v_readlane_b32 s22, v219, 28
	v_add_u32_e32 v0, s9, v120
	v_ashrrev_i32_e32 v1, 31, v0
	v_lshlrev_b64 v[0:1], 12, v[0:1]
	v_lshl_add_u64 v[0:1], s[30:31], 0, v[0:1]
	v_lshl_add_u64 v[0:1], v[0:1], 0, v[96:97]
	v_readlane_b32 s23, v219, 29
	v_readlane_b32 s15, v219, 3
	v_lshlrev_b32_e32 v82, 4, v118
	v_lshl_add_u64 v[64:65], v[0:1], 0, s[22:23]
	v_add_co_u32_e32 v68, vcc, s87, v64
	v_add_u32_e32 v0, s15, v120
	s_nop 0
	v_addc_co_u32_e32 v69, vcc, 0, v65, vcc
	v_ashrrev_i32_e32 v1, 31, v0
	v_add_co_u32_e32 v70, vcc, s66, v64
	v_lshlrev_b64 v[0:1], 12, v[0:1]
	s_nop 0
	v_addc_co_u32_e32 v71, vcc, 0, v65, vcc
	v_lshl_add_u64 v[0:1], s[28:29], 0, v[0:1]
	v_add_co_u32_e32 v72, vcc, s20, v64
	v_lshl_add_u64 v[0:1], v[0:1], 0, v[96:97]
	s_nop 0
	v_addc_co_u32_e32 v73, vcc, 0, v65, vcc
	v_lshl_add_u64 v[66:67], v[0:1], 0, s[22:23]
	global_load_dwordx4 v[0:3], v[64:65], off
	global_load_dwordx4 v[4:7], v[68:69], off
	global_load_dwordx4 v[8:11], v[70:71], off
	global_load_dwordx4 v[12:15], v[72:73], off
	global_load_dwordx4 v[16:19], v[66:67], off
	v_add_co_u32_e32 v74, vcc, s87, v66
	v_lshlrev_b32_e32 v83, 4, v119
	s_nop 0
	v_addc_co_u32_e32 v75, vcc, 0, v67, vcc
	v_add_co_u32_e32 v76, vcc, s66, v66
	global_load_dwordx4 v[20:23], v[74:75], off
	s_nop 0
	v_addc_co_u32_e32 v77, vcc, 0, v67, vcc
	v_add_co_u32_e32 v78, vcc, s20, v66
	global_load_dwordx4 v[24:27], v[76:77], off
	s_nop 0
	v_addc_co_u32_e32 v79, vcc, 0, v67, vcc
	global_load_dwordx4 v[28:31], v[78:79], off
	v_lshlrev_b32_e32 v87, 4, v116
	s_waitcnt vmcnt(7)
	ds_write_b128 v112, v[0:3]
	s_waitcnt vmcnt(6)
	ds_write_b128 v112, v[4:7] offset:4096
	s_waitcnt vmcnt(5)
	ds_write_b128 v112, v[8:11] offset:8192
	s_waitcnt vmcnt(4)
	ds_write_b128 v112, v[12:15] offset:12288
	s_waitcnt vmcnt(3)
	ds_write_b128 v112, v[16:19] offset:16384
	s_waitcnt vmcnt(2)
	ds_write_b128 v112, v[20:23] offset:20480
	s_waitcnt vmcnt(1)
	ds_write_b128 v112, v[24:27] offset:24576
	s_waitcnt vmcnt(0)
	ds_write_b128 v112, v[28:31] offset:28672
	global_load_dwordx4 v[88:91], v[64:65], off offset:128
	global_load_dwordx4 v[92:95], v[68:69], off offset:128
	global_load_dwordx4 v[96:99], v[70:71], off offset:128
	global_load_dwordx4 v[100:103], v[72:73], off offset:128
	global_load_dwordx4 v[104:107], v[66:67], off offset:128
	global_load_dwordx4 v[120:123], v[74:75], off offset:128
	global_load_dwordx4 v[124:127], v[76:77], off offset:128
	global_load_dwordx4 v[128:131], v[78:79], off offset:128
	v_lshlrev_b32_e32 v4, 4, v117
	s_waitcnt lgkmcnt(0)
	s_barrier
	s_setprio 1
	v_or3_b32 v81, v4, v115, v113
	ds_read_b128 v[0:3], v81
	v_or3_b32 v85, v4, v114, v113
	ds_read_b128 v[4:7], v85 offset:16384
	ds_read_b128 v[8:11], v85 offset:20480
	v_or3_b32 v80, v82, v115, v113
	ds_read_b128 v[116:119], v80
	v_or3_b32 v84, v82, v114, v113
	ds_read_b128 v[132:135], v84 offset:16384
	ds_read_b128 v[144:147], v84 offset:20480
	s_waitcnt lgkmcnt(4)
	v_mfma_f32_32x32x16_bf16 v[48:63], v[0:3], v[4:7], 0
	v_or3_b32 v82, v83, v115, v113
	v_or3_b32 v86, v83, v114, v113
	v_or3_b32 v83, v87, v115, v113
	v_or3_b32 v87, v87, v114, v113
	s_waitcnt lgkmcnt(3)
	v_mfma_f32_32x32x16_bf16 v[32:47], v[0:3], v[8:11], 0
	ds_read_b128 v[0:3], v81 offset:4096
	s_waitcnt lgkmcnt(2)
	v_mfma_f32_32x32x16_bf16 v[48:63], v[116:119], v[132:135], v[48:63]
	s_waitcnt lgkmcnt(1)
	v_mfma_f32_32x32x16_bf16 v[32:47], v[116:119], v[144:147], v[32:47]
	ds_read_b128 v[116:119], v80 offset:4096
	s_waitcnt lgkmcnt(1)
	v_mfma_f32_32x32x16_bf16 v[16:31], v[0:3], v[4:7], 0
	v_mfma_f32_32x32x16_bf16 v[0:15], v[0:3], v[8:11], 0
	s_waitcnt lgkmcnt(0)
	v_mfma_f32_32x32x16_bf16 v[16:31], v[116:119], v[132:135], v[16:31]
	ds_read_b128 v[132:135], v86 offset:16384
	v_mfma_f32_32x32x16_bf16 v[0:15], v[116:119], v[144:147], v[0:15]
	ds_read_b128 v[116:119], v82
	ds_read_b128 v[144:147], v86 offset:20480
	s_waitcnt lgkmcnt(1)
	v_mfma_f32_32x32x16_bf16 v[48:63], v[116:119], v[132:135], v[48:63]
	s_waitcnt lgkmcnt(0)
	v_mfma_f32_32x32x16_bf16 v[32:47], v[116:119], v[144:147], v[32:47]
	ds_read_b128 v[116:119], v82 offset:4096
	s_waitcnt lgkmcnt(0)
	v_mfma_f32_32x32x16_bf16 v[16:31], v[116:119], v[132:135], v[16:31]
	ds_read_b128 v[132:135], v87 offset:16384
	v_mfma_f32_32x32x16_bf16 v[0:15], v[116:119], v[144:147], v[0:15]
	ds_read_b128 v[116:119], v83
	ds_read_b128 v[144:147], v87 offset:20480
	s_waitcnt lgkmcnt(1)
	v_mfma_f32_32x32x16_bf16 v[48:63], v[116:119], v[132:135], v[48:63]
	s_waitcnt lgkmcnt(0)
	v_mfma_f32_32x32x16_bf16 v[32:47], v[116:119], v[144:147], v[32:47]
	ds_read_b128 v[114:117], v83 offset:4096
	s_waitcnt lgkmcnt(0)
	v_mfma_f32_32x32x16_bf16 v[16:31], v[114:117], v[132:135], v[16:31]
	v_mfma_f32_32x32x16_bf16 v[0:15], v[114:117], v[144:147], v[0:15]
	s_setprio 0
	s_waitcnt vmcnt(7)
	ds_write_b128 v112, v[88:91] offset:32768
	s_waitcnt vmcnt(6)
	ds_write_b128 v112, v[92:95] offset:36864
	s_waitcnt vmcnt(5)
	ds_write_b128 v112, v[96:99] offset:40960
	s_waitcnt vmcnt(4)
	ds_write_b128 v112, v[100:103] offset:45056
	s_waitcnt vmcnt(3)
	ds_write_b128 v112, v[104:107] offset:49152
	s_waitcnt vmcnt(2)
	ds_write_b128 v112, v[120:123] offset:53248
	s_waitcnt vmcnt(1)
	ds_write_b128 v112, v[124:127] offset:57344
	s_waitcnt vmcnt(0)
	ds_write_b128 v112, v[128:131] offset:61440
	global_load_dwordx4 v[88:91], v[78:79], off offset:256
	global_load_dwordx4 v[92:95], v[76:77], off offset:256
	global_load_dwordx4 v[96:99], v[74:75], off offset:256
	global_load_dwordx4 v[100:103], v[72:73], off offset:256
	global_load_dwordx4 v[104:107], v[70:71], off offset:256
	global_load_dwordx4 v[114:117], v[68:69], off offset:256
	global_load_dwordx4 v[118:121], v[66:67], off offset:256
	global_load_dwordx4 v[122:125], v[64:65], off offset:256
	s_waitcnt lgkmcnt(0)
	s_barrier
	s_setprio 1
	ds_read_b128 v[126:129], v81 offset:32768
	ds_read_b128 v[130:133], v85 offset:49152
	ds_read_b128 v[144:147], v85 offset:53248
	s_waitcnt lgkmcnt(1)
	v_mfma_f32_32x32x16_bf16 v[48:63], v[126:129], v[130:133], v[48:63]
	s_waitcnt lgkmcnt(0)
	v_mfma_f32_32x32x16_bf16 v[32:47], v[126:129], v[144:147], v[32:47]
	ds_read_b128 v[126:129], v81 offset:36864
	s_waitcnt lgkmcnt(0)
	v_mfma_f32_32x32x16_bf16 v[16:31], v[126:129], v[130:133], v[16:31]
	v_mfma_f32_32x32x16_bf16 v[0:15], v[126:129], v[144:147], v[0:15]
	ds_read_b128 v[126:129], v80 offset:32768
	ds_read_b128 v[130:133], v84 offset:49152
	ds_read_b128 v[144:147], v84 offset:53248
	s_waitcnt lgkmcnt(1)
	v_mfma_f32_32x32x16_bf16 v[48:63], v[126:129], v[130:133], v[48:63]
	s_waitcnt lgkmcnt(0)
	v_mfma_f32_32x32x16_bf16 v[32:47], v[126:129], v[144:147], v[32:47]
	ds_read_b128 v[126:129], v80 offset:36864
	s_waitcnt lgkmcnt(0)
	v_mfma_f32_32x32x16_bf16 v[16:31], v[126:129], v[130:133], v[16:31]
	v_mfma_f32_32x32x16_bf16 v[0:15], v[126:129], v[144:147], v[0:15]
	ds_read_b128 v[126:129], v82 offset:32768
	ds_read_b128 v[130:133], v86 offset:49152
	ds_read_b128 v[144:147], v86 offset:53248
	s_waitcnt lgkmcnt(1)
	v_mfma_f32_32x32x16_bf16 v[48:63], v[126:129], v[130:133], v[48:63]
	s_waitcnt lgkmcnt(0)
	v_mfma_f32_32x32x16_bf16 v[32:47], v[126:129], v[144:147], v[32:47]
	ds_read_b128 v[126:129], v82 offset:36864
	s_waitcnt lgkmcnt(0)
	v_mfma_f32_32x32x16_bf16 v[16:31], v[126:129], v[130:133], v[16:31]
	v_mfma_f32_32x32x16_bf16 v[0:15], v[126:129], v[144:147], v[0:15]
	ds_read_b128 v[126:129], v83 offset:32768
	ds_read_b128 v[130:133], v87 offset:49152
	ds_read_b128 v[144:147], v87 offset:53248
	s_waitcnt lgkmcnt(1)
	v_mfma_f32_32x32x16_bf16 v[48:63], v[126:129], v[130:133], v[48:63]
	s_waitcnt lgkmcnt(0)
	v_mfma_f32_32x32x16_bf16 v[32:47], v[126:129], v[144:147], v[32:47]
	ds_read_b128 v[126:129], v83 offset:36864
	s_waitcnt lgkmcnt(0)
	v_mfma_f32_32x32x16_bf16 v[16:31], v[126:129], v[130:133], v[16:31]
	v_mfma_f32_32x32x16_bf16 v[0:15], v[126:129], v[144:147], v[0:15]
	s_setprio 0
	s_waitcnt vmcnt(0)
	ds_write_b128 v112, v[122:125]
	ds_write_b128 v112, v[114:117] offset:4096
	ds_write_b128 v112, v[104:107] offset:8192
	ds_write_b128 v112, v[100:103] offset:12288
	ds_write_b128 v112, v[118:121] offset:16384
	ds_write_b128 v112, v[96:99] offset:20480
	ds_write_b128 v112, v[92:95] offset:24576
	ds_write_b128 v112, v[88:91] offset:28672
	global_load_dwordx4 v[88:91], v[78:79], off offset:384
	global_load_dwordx4 v[92:95], v[76:77], off offset:384
	global_load_dwordx4 v[96:99], v[74:75], off offset:384
	global_load_dwordx4 v[100:103], v[72:73], off offset:384
	global_load_dwordx4 v[104:107], v[70:71], off offset:384
	global_load_dwordx4 v[114:117], v[68:69], off offset:384
	global_load_dwordx4 v[118:121], v[66:67], off offset:384
	global_load_dwordx4 v[122:125], v[64:65], off offset:384
	s_waitcnt lgkmcnt(0)
	s_barrier
	s_setprio 1
	ds_read_b128 v[126:129], v81
	ds_read_b128 v[130:133], v85 offset:16384
	ds_read_b128 v[144:147], v85 offset:20480
	s_waitcnt lgkmcnt(1)
	v_mfma_f32_32x32x16_bf16 v[48:63], v[126:129], v[130:133], v[48:63]
	s_waitcnt lgkmcnt(0)
	v_mfma_f32_32x32x16_bf16 v[32:47], v[126:129], v[144:147], v[32:47]
	ds_read_b128 v[126:129], v81 offset:4096
	s_waitcnt lgkmcnt(0)
	v_mfma_f32_32x32x16_bf16 v[16:31], v[126:129], v[130:133], v[16:31]
	v_mfma_f32_32x32x16_bf16 v[0:15], v[126:129], v[144:147], v[0:15]
	ds_read_b128 v[126:129], v80
	ds_read_b128 v[130:133], v84 offset:16384
	ds_read_b128 v[144:147], v84 offset:20480
	s_waitcnt lgkmcnt(1)
	v_mfma_f32_32x32x16_bf16 v[48:63], v[126:129], v[130:133], v[48:63]
	s_waitcnt lgkmcnt(0)
	v_mfma_f32_32x32x16_bf16 v[32:47], v[126:129], v[144:147], v[32:47]
	ds_read_b128 v[126:129], v80 offset:4096
	s_waitcnt lgkmcnt(0)
	v_mfma_f32_32x32x16_bf16 v[16:31], v[126:129], v[130:133], v[16:31]
	v_mfma_f32_32x32x16_bf16 v[0:15], v[126:129], v[144:147], v[0:15]
	ds_read_b128 v[126:129], v82
	ds_read_b128 v[130:133], v86 offset:16384
	ds_read_b128 v[144:147], v86 offset:20480
	s_waitcnt lgkmcnt(1)
	v_mfma_f32_32x32x16_bf16 v[48:63], v[126:129], v[130:133], v[48:63]
	s_waitcnt lgkmcnt(0)
	v_mfma_f32_32x32x16_bf16 v[32:47], v[126:129], v[144:147], v[32:47]
	ds_read_b128 v[126:129], v82 offset:4096
	s_waitcnt lgkmcnt(0)
	v_mfma_f32_32x32x16_bf16 v[16:31], v[126:129], v[130:133], v[16:31]
	v_mfma_f32_32x32x16_bf16 v[0:15], v[126:129], v[144:147], v[0:15]
	ds_read_b128 v[126:129], v83
	ds_read_b128 v[130:133], v87 offset:16384
	ds_read_b128 v[144:147], v87 offset:20480
	s_waitcnt lgkmcnt(1)
	v_mfma_f32_32x32x16_bf16 v[48:63], v[126:129], v[130:133], v[48:63]
	s_waitcnt lgkmcnt(0)
	v_mfma_f32_32x32x16_bf16 v[32:47], v[126:129], v[144:147], v[32:47]
	ds_read_b128 v[126:129], v83 offset:4096
	s_waitcnt lgkmcnt(0)
	v_mfma_f32_32x32x16_bf16 v[16:31], v[126:129], v[130:133], v[16:31]
	v_mfma_f32_32x32x16_bf16 v[0:15], v[126:129], v[144:147], v[0:15]
	s_setprio 0
	s_waitcnt vmcnt(0)
	ds_write_b128 v112, v[122:125] offset:32768
	ds_write_b128 v112, v[114:117] offset:36864
	ds_write_b128 v112, v[104:107] offset:40960
	ds_write_b128 v112, v[100:103] offset:45056
	ds_write_b128 v112, v[118:121] offset:49152
	ds_write_b128 v112, v[96:99] offset:53248
	ds_write_b128 v112, v[92:95] offset:57344
	ds_write_b128 v112, v[88:91] offset:61440
	global_load_dwordx4 v[88:91], v[78:79], off offset:512
	global_load_dwordx4 v[92:95], v[76:77], off offset:512
	global_load_dwordx4 v[96:99], v[74:75], off offset:512
	global_load_dwordx4 v[100:103], v[72:73], off offset:512
	global_load_dwordx4 v[104:107], v[70:71], off offset:512
	global_load_dwordx4 v[114:117], v[68:69], off offset:512
	global_load_dwordx4 v[118:121], v[66:67], off offset:512
	global_load_dwordx4 v[122:125], v[64:65], off offset:512
	s_waitcnt lgkmcnt(0)
	s_barrier
	s_setprio 1
	ds_read_b128 v[126:129], v81 offset:32768
	ds_read_b128 v[130:133], v85 offset:49152
	ds_read_b128 v[144:147], v85 offset:53248
	s_waitcnt lgkmcnt(1)
	v_mfma_f32_32x32x16_bf16 v[48:63], v[126:129], v[130:133], v[48:63]
	s_waitcnt lgkmcnt(0)
	v_mfma_f32_32x32x16_bf16 v[32:47], v[126:129], v[144:147], v[32:47]
	ds_read_b128 v[126:129], v81 offset:36864
	s_waitcnt lgkmcnt(0)
	v_mfma_f32_32x32x16_bf16 v[16:31], v[126:129], v[130:133], v[16:31]
	v_mfma_f32_32x32x16_bf16 v[0:15], v[126:129], v[144:147], v[0:15]
	ds_read_b128 v[126:129], v80 offset:32768
	ds_read_b128 v[130:133], v84 offset:49152
	ds_read_b128 v[144:147], v84 offset:53248
	s_waitcnt lgkmcnt(1)
	v_mfma_f32_32x32x16_bf16 v[48:63], v[126:129], v[130:133], v[48:63]
	s_waitcnt lgkmcnt(0)
	v_mfma_f32_32x32x16_bf16 v[32:47], v[126:129], v[144:147], v[32:47]
	ds_read_b128 v[126:129], v80 offset:36864
	s_waitcnt lgkmcnt(0)
	v_mfma_f32_32x32x16_bf16 v[16:31], v[126:129], v[130:133], v[16:31]
	v_mfma_f32_32x32x16_bf16 v[0:15], v[126:129], v[144:147], v[0:15]
	ds_read_b128 v[126:129], v82 offset:32768
	ds_read_b128 v[130:133], v86 offset:49152
	ds_read_b128 v[144:147], v86 offset:53248
	s_waitcnt lgkmcnt(1)
	v_mfma_f32_32x32x16_bf16 v[48:63], v[126:129], v[130:133], v[48:63]
	s_waitcnt lgkmcnt(0)
	v_mfma_f32_32x32x16_bf16 v[32:47], v[126:129], v[144:147], v[32:47]
	ds_read_b128 v[126:129], v82 offset:36864
	s_waitcnt lgkmcnt(0)
	v_mfma_f32_32x32x16_bf16 v[16:31], v[126:129], v[130:133], v[16:31]
	v_mfma_f32_32x32x16_bf16 v[0:15], v[126:129], v[144:147], v[0:15]
	ds_read_b128 v[126:129], v83 offset:32768
	ds_read_b128 v[130:133], v87 offset:49152
	ds_read_b128 v[144:147], v87 offset:53248
	s_waitcnt lgkmcnt(1)
	v_mfma_f32_32x32x16_bf16 v[48:63], v[126:129], v[130:133], v[48:63]
	s_waitcnt lgkmcnt(0)
	v_mfma_f32_32x32x16_bf16 v[32:47], v[126:129], v[144:147], v[32:47]
	ds_read_b128 v[126:129], v83 offset:36864
	s_waitcnt lgkmcnt(0)
	v_mfma_f32_32x32x16_bf16 v[16:31], v[126:129], v[130:133], v[16:31]
	v_mfma_f32_32x32x16_bf16 v[0:15], v[126:129], v[144:147], v[0:15]
	s_setprio 0
	s_waitcnt vmcnt(0)
	ds_write_b128 v112, v[122:125]
	ds_write_b128 v112, v[114:117] offset:4096
	ds_write_b128 v112, v[104:107] offset:8192
	ds_write_b128 v112, v[100:103] offset:12288
	ds_write_b128 v112, v[118:121] offset:16384
	ds_write_b128 v112, v[96:99] offset:20480
	ds_write_b128 v112, v[92:95] offset:24576
	ds_write_b128 v112, v[88:91] offset:28672
	global_load_dwordx4 v[88:91], v[78:79], off offset:640
	global_load_dwordx4 v[92:95], v[76:77], off offset:640
	global_load_dwordx4 v[96:99], v[74:75], off offset:640
	global_load_dwordx4 v[100:103], v[72:73], off offset:640
	global_load_dwordx4 v[104:107], v[70:71], off offset:640
	global_load_dwordx4 v[114:117], v[68:69], off offset:640
	global_load_dwordx4 v[118:121], v[66:67], off offset:640
	global_load_dwordx4 v[122:125], v[64:65], off offset:640
	s_waitcnt lgkmcnt(0)
	s_barrier
	s_setprio 1
	ds_read_b128 v[126:129], v81
	ds_read_b128 v[130:133], v85 offset:16384
	ds_read_b128 v[144:147], v85 offset:20480
	s_waitcnt lgkmcnt(1)
	v_mfma_f32_32x32x16_bf16 v[48:63], v[126:129], v[130:133], v[48:63]
	s_waitcnt lgkmcnt(0)
	v_mfma_f32_32x32x16_bf16 v[32:47], v[126:129], v[144:147], v[32:47]
	ds_read_b128 v[126:129], v81 offset:4096
	s_waitcnt lgkmcnt(0)
	v_mfma_f32_32x32x16_bf16 v[16:31], v[126:129], v[130:133], v[16:31]
	v_mfma_f32_32x32x16_bf16 v[0:15], v[126:129], v[144:147], v[0:15]
	ds_read_b128 v[126:129], v80
	ds_read_b128 v[130:133], v84 offset:16384
	ds_read_b128 v[144:147], v84 offset:20480
	s_waitcnt lgkmcnt(1)
	v_mfma_f32_32x32x16_bf16 v[48:63], v[126:129], v[130:133], v[48:63]
	s_waitcnt lgkmcnt(0)
	v_mfma_f32_32x32x16_bf16 v[32:47], v[126:129], v[144:147], v[32:47]
	ds_read_b128 v[126:129], v80 offset:4096
	s_waitcnt lgkmcnt(0)
	v_mfma_f32_32x32x16_bf16 v[16:31], v[126:129], v[130:133], v[16:31]
	v_mfma_f32_32x32x16_bf16 v[0:15], v[126:129], v[144:147], v[0:15]
	ds_read_b128 v[126:129], v82
	ds_read_b128 v[130:133], v86 offset:16384
	ds_read_b128 v[144:147], v86 offset:20480
	s_waitcnt lgkmcnt(1)
	v_mfma_f32_32x32x16_bf16 v[48:63], v[126:129], v[130:133], v[48:63]
	s_waitcnt lgkmcnt(0)
	v_mfma_f32_32x32x16_bf16 v[32:47], v[126:129], v[144:147], v[32:47]
	ds_read_b128 v[126:129], v82 offset:4096
	s_waitcnt lgkmcnt(0)
	v_mfma_f32_32x32x16_bf16 v[16:31], v[126:129], v[130:133], v[16:31]
	v_mfma_f32_32x32x16_bf16 v[0:15], v[126:129], v[144:147], v[0:15]
	ds_read_b128 v[126:129], v83
	ds_read_b128 v[130:133], v87 offset:16384
	ds_read_b128 v[144:147], v87 offset:20480
	s_waitcnt lgkmcnt(1)
	v_mfma_f32_32x32x16_bf16 v[48:63], v[126:129], v[130:133], v[48:63]
	s_waitcnt lgkmcnt(0)
	v_mfma_f32_32x32x16_bf16 v[32:47], v[126:129], v[144:147], v[32:47]
	ds_read_b128 v[126:129], v83 offset:4096
	s_waitcnt lgkmcnt(0)
	v_mfma_f32_32x32x16_bf16 v[16:31], v[126:129], v[130:133], v[16:31]
	v_mfma_f32_32x32x16_bf16 v[0:15], v[126:129], v[144:147], v[0:15]
	s_setprio 0
	s_waitcnt vmcnt(0)
	ds_write_b128 v112, v[122:125] offset:32768
	ds_write_b128 v112, v[114:117] offset:36864
	ds_write_b128 v112, v[104:107] offset:40960
	ds_write_b128 v112, v[100:103] offset:45056
	ds_write_b128 v112, v[118:121] offset:49152
	ds_write_b128 v112, v[96:99] offset:53248
	ds_write_b128 v112, v[92:95] offset:57344
	ds_write_b128 v112, v[88:91] offset:61440
	global_load_dwordx4 v[88:91], v[78:79], off offset:768
	global_load_dwordx4 v[92:95], v[76:77], off offset:768
	global_load_dwordx4 v[96:99], v[74:75], off offset:768
	global_load_dwordx4 v[100:103], v[72:73], off offset:768
	global_load_dwordx4 v[104:107], v[70:71], off offset:768
	global_load_dwordx4 v[114:117], v[68:69], off offset:768
	global_load_dwordx4 v[118:121], v[66:67], off offset:768
	global_load_dwordx4 v[122:125], v[64:65], off offset:768
	s_waitcnt lgkmcnt(0)
	s_barrier
	s_setprio 1
	ds_read_b128 v[126:129], v81 offset:32768
	ds_read_b128 v[130:133], v85 offset:49152
	ds_read_b128 v[144:147], v85 offset:53248
	s_waitcnt lgkmcnt(1)
	v_mfma_f32_32x32x16_bf16 v[48:63], v[126:129], v[130:133], v[48:63]
	s_waitcnt lgkmcnt(0)
	v_mfma_f32_32x32x16_bf16 v[32:47], v[126:129], v[144:147], v[32:47]
	ds_read_b128 v[126:129], v81 offset:36864
	s_waitcnt lgkmcnt(0)
	v_mfma_f32_32x32x16_bf16 v[16:31], v[126:129], v[130:133], v[16:31]
	v_mfma_f32_32x32x16_bf16 v[0:15], v[126:129], v[144:147], v[0:15]
	ds_read_b128 v[126:129], v80 offset:32768
	ds_read_b128 v[130:133], v84 offset:49152
	ds_read_b128 v[144:147], v84 offset:53248
	s_waitcnt lgkmcnt(1)
	v_mfma_f32_32x32x16_bf16 v[48:63], v[126:129], v[130:133], v[48:63]
	s_waitcnt lgkmcnt(0)
	v_mfma_f32_32x32x16_bf16 v[32:47], v[126:129], v[144:147], v[32:47]
	ds_read_b128 v[126:129], v80 offset:36864
	s_waitcnt lgkmcnt(0)
	v_mfma_f32_32x32x16_bf16 v[16:31], v[126:129], v[130:133], v[16:31]
	v_mfma_f32_32x32x16_bf16 v[0:15], v[126:129], v[144:147], v[0:15]
	ds_read_b128 v[126:129], v82 offset:32768
	ds_read_b128 v[130:133], v86 offset:49152
	ds_read_b128 v[144:147], v86 offset:53248
	s_waitcnt lgkmcnt(1)
	v_mfma_f32_32x32x16_bf16 v[48:63], v[126:129], v[130:133], v[48:63]
	s_waitcnt lgkmcnt(0)
	v_mfma_f32_32x32x16_bf16 v[32:47], v[126:129], v[144:147], v[32:47]
	ds_read_b128 v[126:129], v82 offset:36864
	s_waitcnt lgkmcnt(0)
	v_mfma_f32_32x32x16_bf16 v[16:31], v[126:129], v[130:133], v[16:31]
	v_mfma_f32_32x32x16_bf16 v[0:15], v[126:129], v[144:147], v[0:15]
	ds_read_b128 v[126:129], v83 offset:32768
	ds_read_b128 v[130:133], v87 offset:49152
	ds_read_b128 v[144:147], v87 offset:53248
	s_waitcnt lgkmcnt(1)
	v_mfma_f32_32x32x16_bf16 v[48:63], v[126:129], v[130:133], v[48:63]
	s_waitcnt lgkmcnt(0)
	v_mfma_f32_32x32x16_bf16 v[32:47], v[126:129], v[144:147], v[32:47]
	ds_read_b128 v[126:129], v83 offset:36864
	s_waitcnt lgkmcnt(0)
	v_mfma_f32_32x32x16_bf16 v[16:31], v[126:129], v[130:133], v[16:31]
	v_mfma_f32_32x32x16_bf16 v[0:15], v[126:129], v[144:147], v[0:15]
	s_setprio 0
	s_waitcnt vmcnt(0)
	ds_write_b128 v112, v[122:125]
	ds_write_b128 v112, v[114:117] offset:4096
	ds_write_b128 v112, v[104:107] offset:8192
	ds_write_b128 v112, v[100:103] offset:12288
	ds_write_b128 v112, v[118:121] offset:16384
	ds_write_b128 v112, v[96:99] offset:20480
	ds_write_b128 v112, v[92:95] offset:24576
	ds_write_b128 v112, v[88:91] offset:28672
	global_load_dwordx4 v[88:91], v[78:79], off offset:896
	s_nop 0
	global_load_dwordx4 v[76:79], v[76:77], off offset:896
	s_nop 0
	global_load_dwordx4 v[92:95], v[74:75], off offset:896
	s_nop 0
	global_load_dwordx4 v[72:75], v[72:73], off offset:896
	s_nop 0
	global_load_dwordx4 v[96:99], v[70:71], off offset:896
	s_nop 0
	global_load_dwordx4 v[68:71], v[68:69], off offset:896
	s_nop 0
	global_load_dwordx4 v[100:103], v[66:67], off offset:896
	s_nop 0
	global_load_dwordx4 v[64:67], v[64:65], off offset:896
	s_waitcnt lgkmcnt(0)
	s_barrier
	s_setprio 1
	ds_read_b128 v[104:107], v81
	ds_read_b128 v[114:117], v85 offset:16384
	ds_read_b128 v[118:121], v85 offset:20480
	s_waitcnt lgkmcnt(1)
	v_mfma_f32_32x32x16_bf16 v[48:63], v[104:107], v[114:117], v[48:63]
	s_waitcnt lgkmcnt(0)
	v_mfma_f32_32x32x16_bf16 v[32:47], v[104:107], v[118:121], v[32:47]
	ds_read_b128 v[104:107], v81 offset:4096
	s_waitcnt lgkmcnt(0)
	v_mfma_f32_32x32x16_bf16 v[16:31], v[104:107], v[114:117], v[16:31]
	v_mfma_f32_32x32x16_bf16 v[0:15], v[104:107], v[118:121], v[0:15]
	ds_read_b128 v[104:107], v80
	ds_read_b128 v[114:117], v84 offset:16384
	ds_read_b128 v[118:121], v84 offset:20480
	s_waitcnt lgkmcnt(1)
	v_mfma_f32_32x32x16_bf16 v[48:63], v[104:107], v[114:117], v[48:63]
	s_waitcnt lgkmcnt(0)
	v_mfma_f32_32x32x16_bf16 v[32:47], v[104:107], v[118:121], v[32:47]
	ds_read_b128 v[104:107], v80 offset:4096
	s_waitcnt lgkmcnt(0)
	v_mfma_f32_32x32x16_bf16 v[16:31], v[104:107], v[114:117], v[16:31]
	v_mfma_f32_32x32x16_bf16 v[0:15], v[104:107], v[118:121], v[0:15]
	ds_read_b128 v[104:107], v82
	ds_read_b128 v[114:117], v86 offset:16384
	ds_read_b128 v[118:121], v86 offset:20480
	s_waitcnt lgkmcnt(1)
	v_mfma_f32_32x32x16_bf16 v[48:63], v[104:107], v[114:117], v[48:63]
	s_waitcnt lgkmcnt(0)
	v_mfma_f32_32x32x16_bf16 v[32:47], v[104:107], v[118:121], v[32:47]
	ds_read_b128 v[104:107], v82 offset:4096
	s_waitcnt lgkmcnt(0)
	v_mfma_f32_32x32x16_bf16 v[16:31], v[104:107], v[114:117], v[16:31]
	v_mfma_f32_32x32x16_bf16 v[0:15], v[104:107], v[118:121], v[0:15]
	ds_read_b128 v[104:107], v83
	ds_read_b128 v[114:117], v87 offset:16384
	ds_read_b128 v[118:121], v87 offset:20480
	s_waitcnt lgkmcnt(1)
	v_mfma_f32_32x32x16_bf16 v[48:63], v[104:107], v[114:117], v[48:63]
	s_waitcnt lgkmcnt(0)
	v_mfma_f32_32x32x16_bf16 v[32:47], v[104:107], v[118:121], v[32:47]
	ds_read_b128 v[104:107], v83 offset:4096
	s_waitcnt lgkmcnt(0)
	v_mfma_f32_32x32x16_bf16 v[16:31], v[104:107], v[114:117], v[16:31]
	v_mfma_f32_32x32x16_bf16 v[0:15], v[104:107], v[118:121], v[0:15]
	s_setprio 0
	s_waitcnt vmcnt(0)
	ds_write_b128 v112, v[64:67] offset:32768
	ds_write_b128 v112, v[68:71] offset:36864
	ds_write_b128 v112, v[96:99] offset:40960
	ds_write_b128 v112, v[72:75] offset:45056
	ds_write_b128 v112, v[100:103] offset:49152
	ds_write_b128 v112, v[92:95] offset:53248
	ds_write_b128 v112, v[76:79] offset:57344
	ds_write_b128 v112, v[88:91] offset:61440
	s_waitcnt lgkmcnt(0)
	s_barrier
	s_setprio 1
	ds_read_b128 v[64:67], v81 offset:32768
	ds_read_b128 v[68:71], v85 offset:49152
	ds_read_b128 v[72:75], v85 offset:53248
	s_waitcnt lgkmcnt(1)
	v_mfma_f32_32x32x16_bf16 v[48:63], v[64:67], v[68:71], v[48:63]
	s_waitcnt lgkmcnt(0)
	v_mfma_f32_32x32x16_bf16 v[32:47], v[64:67], v[72:75], v[32:47]
	ds_read_b128 v[64:67], v81 offset:36864
	s_waitcnt lgkmcnt(0)
	v_mfma_f32_32x32x16_bf16 v[16:31], v[64:67], v[68:71], v[16:31]
	v_mfma_f32_32x32x16_bf16 v[0:15], v[64:67], v[72:75], v[0:15]
	ds_read_b128 v[64:67], v80 offset:32768
	ds_read_b128 v[68:71], v84 offset:49152
	ds_read_b128 v[72:75], v84 offset:53248
	s_waitcnt lgkmcnt(1)
	v_mfma_f32_32x32x16_bf16 v[48:63], v[64:67], v[68:71], v[48:63]
	s_waitcnt lgkmcnt(0)
	v_mfma_f32_32x32x16_bf16 v[32:47], v[64:67], v[72:75], v[32:47]
	ds_read_b128 v[64:67], v80 offset:36864
	s_waitcnt lgkmcnt(0)
	v_mfma_f32_32x32x16_bf16 v[16:31], v[64:67], v[68:71], v[16:31]
	v_mfma_f32_32x32x16_bf16 v[0:15], v[64:67], v[72:75], v[0:15]
	ds_read_b128 v[64:67], v82 offset:32768
	ds_read_b128 v[68:71], v86 offset:49152
	ds_read_b128 v[72:75], v86 offset:53248
	s_waitcnt lgkmcnt(1)
	v_mfma_f32_32x32x16_bf16 v[48:63], v[64:67], v[68:71], v[48:63]
	s_waitcnt lgkmcnt(0)
	v_mfma_f32_32x32x16_bf16 v[32:47], v[64:67], v[72:75], v[32:47]
	ds_read_b128 v[64:67], v82 offset:36864
	s_waitcnt lgkmcnt(0)
	v_mfma_f32_32x32x16_bf16 v[16:31], v[64:67], v[68:71], v[16:31]
	v_mfma_f32_32x32x16_bf16 v[0:15], v[64:67], v[72:75], v[0:15]
	ds_read_b128 v[64:67], v83 offset:32768
	ds_read_b128 v[68:71], v87 offset:49152
	ds_read_b128 v[72:75], v87 offset:53248
	s_waitcnt lgkmcnt(1)
	v_mfma_f32_32x32x16_bf16 v[48:63], v[64:67], v[68:71], v[48:63]
	s_waitcnt lgkmcnt(0)
	v_mfma_f32_32x32x16_bf16 v[32:47], v[64:67], v[72:75], v[32:47]
	ds_read_b128 v[64:67], v83 offset:36864
	s_waitcnt lgkmcnt(0)
	v_mfma_f32_32x32x16_bf16 v[16:31], v[64:67], v[68:71], v[16:31]
	v_mfma_f32_32x32x16_bf16 v[0:15], v[64:67], v[72:75], v[0:15]
	s_setprio 0
	v_readfirstlane_b32 s8, v111
	v_readfirstlane_b32 s4, v110
	s_lshl_b32 s8, s8, 6
	s_waitcnt lgkmcnt(0)
	s_barrier
	s_add_i32 s8, s8, s15
	s_lshl_b32 s15, s4, 6
	s_add_i32 s15, s15, s9
	v_or_b32_e32 v65, s8, v109
	s_movk_i32 s4, 0x800
	v_cmp_gt_i32_e64 s[38:39], s4, v65
	v_add_u32_e32 v64, 0x1000, v65
	v_lshl_or_b32 v66, v108, 2, s15
	v_or_b32_e32 v84, 32, v65
	s_movk_i32 s4, 0x800
	v_cmp_gt_i32_e32 vcc, s4, v84
	s_mov_b64 s[8:9], exec
	v_lshlrev_b32_e32 v90, 2, v64
	s_and_b64 exec, s[8:9], s[38:39]
	s_mov_b32 s4, s15
	s_add_i32 s22, s4, 0xffffe000
	s_lshr_b32 s22, s22, 3
	s_add_i32 s22, s22, 4
	s_ashr_i32 s23, s15, 11
	s_cmpk_lt_i32 s4, 0x2000
	s_cselect_b32 s22, s23, s22
	s_mul_i32 s22, s22, 0xc000
	v_add_u32_e32 v84, s22, v90
	global_load_dword v68, v84, s[26:27]
	s_add_i32 s4, s15, 8
	s_add_i32 s22, s4, 0xffffe000
	s_lshr_b32 s22, s22, 3
	s_add_i32 s22, s22, 4
	s_ashr_i32 s23, s15, 11
	s_cmpk_lt_i32 s4, 0x2000
	s_cselect_b32 s22, s23, s22
	s_mul_i32 s22, s22, 0xc000
	v_add_u32_e32 v85, s22, v90
	global_load_dword v69, v85, s[26:27]
	s_add_i32 s4, s15, 16
	s_add_i32 s22, s4, 0xffffe000
	s_lshr_b32 s22, s22, 3
	s_add_i32 s22, s22, 4
	s_ashr_i32 s23, s15, 11
	s_cmpk_lt_i32 s4, 0x2000
	s_cselect_b32 s22, s23, s22
	s_mul_i32 s22, s22, 0xc000
	v_add_u32_e32 v84, s22, v90
	global_load_dword v70, v84, s[26:27]
	s_add_i32 s4, s15, 24
	s_add_i32 s22, s4, 0xffffe000
	s_lshr_b32 s22, s22, 3
	s_add_i32 s22, s22, 4
	s_ashr_i32 s23, s15, 11
	s_cmpk_lt_i32 s4, 0x2000
	s_cselect_b32 s22, s23, s22
	s_mul_i32 s22, s22, 0xc000
	v_add_u32_e32 v85, s22, v90
	global_load_dword v71, v85, s[26:27]
	s_add_i32 s4, s15, 32
	s_add_i32 s22, s4, 0xffffe000
	s_lshr_b32 s22, s22, 3
	s_add_i32 s22, s22, 4
	s_ashr_i32 s23, s15, 11
	s_cmpk_lt_i32 s4, 0x2000
	s_cselect_b32 s22, s23, s22
	s_mul_i32 s22, s22, 0xc000
	v_add_u32_e32 v84, s22, v90
	global_load_dword v76, v84, s[26:27]
	s_add_i32 s4, s15, 40
	s_add_i32 s22, s4, 0xffffe000
	s_lshr_b32 s22, s22, 3
	s_add_i32 s22, s22, 4
	s_ashr_i32 s23, s15, 11
	s_cmpk_lt_i32 s4, 0x2000
	s_cselect_b32 s22, s23, s22
	s_mul_i32 s22, s22, 0xc000
	v_add_u32_e32 v85, s22, v90
	global_load_dword v77, v85, s[26:27]
	s_add_i32 s4, s15, 48
	s_add_i32 s22, s4, 0xffffe000
	s_lshr_b32 s22, s22, 3
	s_add_i32 s22, s22, 4
	s_ashr_i32 s23, s15, 11
	s_cmpk_lt_i32 s4, 0x2000
	s_cselect_b32 s22, s23, s22
	s_mul_i32 s22, s22, 0xc000
	v_add_u32_e32 v84, s22, v90
	global_load_dword v78, v84, s[26:27]
	s_add_i32 s4, s15, 56
	s_add_i32 s22, s4, 0xffffe000
	s_lshr_b32 s22, s22, 3
	s_add_i32 s22, s22, 4
	s_ashr_i32 s23, s15, 11
	s_cmpk_lt_i32 s4, 0x2000
	s_cselect_b32 s22, s23, s22
	s_mul_i32 s22, s22, 0xc000
	v_add_u32_e32 v85, s22, v90
	global_load_dword v79, v85, s[26:27]
	s_and_b64 exec, s[8:9], vcc
	s_mov_b32 s4, s15
	s_add_i32 s22, s4, 0xffffe000
	s_lshr_b32 s22, s22, 3
	s_add_i32 s22, s22, 4
	s_ashr_i32 s23, s15, 11
	s_cmpk_lt_i32 s4, 0x2000
	s_cselect_b32 s22, s23, s22
	s_mul_i32 s22, s22, 0xc000
	v_add_u32_e32 v84, s22, v90
	global_load_dword v72, v84, s[26:27] offset:128
	s_add_i32 s4, s15, 8
	s_add_i32 s22, s4, 0xffffe000
	s_lshr_b32 s22, s22, 3
	s_add_i32 s22, s22, 4
	s_ashr_i32 s23, s15, 11
	s_cmpk_lt_i32 s4, 0x2000
	s_cselect_b32 s22, s23, s22
	s_mul_i32 s22, s22, 0xc000
	v_add_u32_e32 v85, s22, v90
	global_load_dword v73, v85, s[26:27] offset:128
	s_add_i32 s4, s15, 16
	s_add_i32 s22, s4, 0xffffe000
	s_lshr_b32 s22, s22, 3
	s_add_i32 s22, s22, 4
	s_ashr_i32 s23, s15, 11
	s_cmpk_lt_i32 s4, 0x2000
	s_cselect_b32 s22, s23, s22
	s_mul_i32 s22, s22, 0xc000
	v_add_u32_e32 v84, s22, v90
	global_load_dword v74, v84, s[26:27] offset:128
	s_add_i32 s4, s15, 24
	s_add_i32 s22, s4, 0xffffe000
	s_lshr_b32 s22, s22, 3
	s_add_i32 s22, s22, 4
	s_ashr_i32 s23, s15, 11
	s_cmpk_lt_i32 s4, 0x2000
	s_cselect_b32 s22, s23, s22
	s_mul_i32 s22, s22, 0xc000
	v_add_u32_e32 v85, s22, v90
	global_load_dword v75, v85, s[26:27] offset:128
	s_add_i32 s4, s15, 32
	s_add_i32 s22, s4, 0xffffe000
	s_lshr_b32 s22, s22, 3
	s_add_i32 s22, s22, 4
	s_ashr_i32 s23, s15, 11
	s_cmpk_lt_i32 s4, 0x2000
	s_cselect_b32 s22, s23, s22
	s_mul_i32 s22, s22, 0xc000
	v_add_u32_e32 v84, s22, v90
	global_load_dword v80, v84, s[26:27] offset:128
	s_add_i32 s4, s15, 40
	s_add_i32 s22, s4, 0xffffe000
	s_lshr_b32 s22, s22, 3
	s_add_i32 s22, s22, 4
	s_ashr_i32 s23, s15, 11
	s_cmpk_lt_i32 s4, 0x2000
	s_cselect_b32 s22, s23, s22
	s_mul_i32 s22, s22, 0xc000
	v_add_u32_e32 v85, s22, v90
	global_load_dword v81, v85, s[26:27] offset:128
	s_add_i32 s4, s15, 48
	s_add_i32 s22, s4, 0xffffe000
	s_lshr_b32 s22, s22, 3
	s_add_i32 s22, s22, 4
	s_ashr_i32 s23, s15, 11
	s_cmpk_lt_i32 s4, 0x2000
	s_cselect_b32 s22, s23, s22
	s_mul_i32 s22, s22, 0xc000
	v_add_u32_e32 v84, s22, v90
	global_load_dword v82, v84, s[26:27] offset:128
	s_add_i32 s4, s15, 56
	s_add_i32 s22, s4, 0xffffe000
	s_lshr_b32 s22, s22, 3
	s_add_i32 s22, s22, 4
	s_ashr_i32 s23, s15, 11
	s_cmpk_lt_i32 s4, 0x2000
	s_cselect_b32 s22, s23, s22
	s_mul_i32 s22, s22, 0xc000
	v_add_u32_e32 v85, s22, v90
	global_load_dword v83, v85, s[26:27] offset:128
	s_mov_b64 exec, s[8:9]
	s_barrier
	v_lshl_add_u32 v88, v66, 11, v65
	v_lshlrev_b32_e32 v88, 2, v88
	s_waitcnt vmcnt(0)
	s_and_b64 exec, s[8:9], s[38:39]
	v_mul_f32_e32 v48, v48, v68
	global_atomic_add_f32 v88, v48, s[0:1]
	v_mul_f32_e32 v49, v49, v68
	v_add_u32_e32 v84, 0x2000, v88
	global_atomic_add_f32 v84, v49, s[0:1]
	v_mul_f32_e32 v50, v50, v68
	v_add_u32_e32 v85, 0x4000, v88
	global_atomic_add_f32 v85, v50, s[0:1]
	v_mul_f32_e32 v51, v51, v68
	v_add_u32_e32 v86, 0x6000, v88
	global_atomic_add_f32 v86, v51, s[0:1]
	v_mul_f32_e32 v52, v52, v69
	v_add_u32_e32 v87, 0x10000, v88
	global_atomic_add_f32 v87, v52, s[0:1]
	v_mul_f32_e32 v53, v53, v69
	v_add_u32_e32 v84, 0x12000, v88
	global_atomic_add_f32 v84, v53, s[0:1]
	v_mul_f32_e32 v54, v54, v69
	v_add_u32_e32 v85, 0x14000, v88
	global_atomic_add_f32 v85, v54, s[0:1]
	v_mul_f32_e32 v55, v55, v69
	v_add_u32_e32 v86, 0x16000, v88
	global_atomic_add_f32 v86, v55, s[0:1]
	v_mul_f32_e32 v56, v56, v70
	v_add_u32_e32 v87, 0x20000, v88
	global_atomic_add_f32 v87, v56, s[0:1]
	v_mul_f32_e32 v57, v57, v70
	v_add_u32_e32 v84, 0x22000, v88
	global_atomic_add_f32 v84, v57, s[0:1]
	v_mul_f32_e32 v58, v58, v70
	v_add_u32_e32 v85, 0x24000, v88
	global_atomic_add_f32 v85, v58, s[0:1]
	v_mul_f32_e32 v59, v59, v70
	v_add_u32_e32 v86, 0x26000, v88
	global_atomic_add_f32 v86, v59, s[0:1]
	v_mul_f32_e32 v60, v60, v71
	v_add_u32_e32 v87, 0x30000, v88
	global_atomic_add_f32 v87, v60, s[0:1]
	v_mul_f32_e32 v61, v61, v71
	v_add_u32_e32 v84, 0x32000, v88
	global_atomic_add_f32 v84, v61, s[0:1]
	v_mul_f32_e32 v62, v62, v71
	v_add_u32_e32 v85, 0x34000, v88
	global_atomic_add_f32 v85, v62, s[0:1]
	v_mul_f32_e32 v63, v63, v71
	v_add_u32_e32 v86, 0x36000, v88
	global_atomic_add_f32 v86, v63, s[0:1]
	s_and_b64 exec, s[8:9], vcc
	v_mul_f32_e32 v32, v32, v72
	global_atomic_add_f32 v88, v32, s[0:1] offset:128
	v_mul_f32_e32 v33, v33, v72
	v_add_u32_e32 v87, 0x2000, v88
	global_atomic_add_f32 v87, v33, s[0:1] offset:128
	v_mul_f32_e32 v34, v34, v72
	v_add_u32_e32 v84, 0x4000, v88
	global_atomic_add_f32 v84, v34, s[0:1] offset:128
	v_mul_f32_e32 v35, v35, v72
	v_add_u32_e32 v85, 0x6000, v88
	global_atomic_add_f32 v85, v35, s[0:1] offset:128
	v_mul_f32_e32 v36, v36, v73
	v_add_u32_e32 v86, 0x10000, v88
	global_atomic_add_f32 v86, v36, s[0:1] offset:128
	v_mul_f32_e32 v37, v37, v73
	v_add_u32_e32 v87, 0x12000, v88
	global_atomic_add_f32 v87, v37, s[0:1] offset:128
	v_mul_f32_e32 v38, v38, v73
	v_add_u32_e32 v84, 0x14000, v88
	global_atomic_add_f32 v84, v38, s[0:1] offset:128
	v_mul_f32_e32 v39, v39, v73
	v_add_u32_e32 v85, 0x16000, v88
	global_atomic_add_f32 v85, v39, s[0:1] offset:128
	v_mul_f32_e32 v40, v40, v74
	v_add_u32_e32 v86, 0x20000, v88
	global_atomic_add_f32 v86, v40, s[0:1] offset:128
	v_mul_f32_e32 v41, v41, v74
	v_add_u32_e32 v87, 0x22000, v88
	global_atomic_add_f32 v87, v41, s[0:1] offset:128
	v_mul_f32_e32 v42, v42, v74
	v_add_u32_e32 v84, 0x24000, v88
	global_atomic_add_f32 v84, v42, s[0:1] offset:128
	v_mul_f32_e32 v43, v43, v74
	v_add_u32_e32 v85, 0x26000, v88
	global_atomic_add_f32 v85, v43, s[0:1] offset:128
	v_mul_f32_e32 v44, v44, v75
	v_add_u32_e32 v86, 0x30000, v88
	global_atomic_add_f32 v86, v44, s[0:1] offset:128
	v_mul_f32_e32 v45, v45, v75
	v_add_u32_e32 v87, 0x32000, v88
	global_atomic_add_f32 v87, v45, s[0:1] offset:128
	v_mul_f32_e32 v46, v46, v75
	v_add_u32_e32 v84, 0x34000, v88
	global_atomic_add_f32 v84, v46, s[0:1] offset:128
	v_mul_f32_e32 v47, v47, v75
	v_add_u32_e32 v85, 0x36000, v88
	global_atomic_add_f32 v85, v47, s[0:1] offset:128
	s_and_b64 exec, s[8:9], s[38:39]
	v_mul_f32_e32 v16, v16, v76
	v_add_u32_e32 v86, 0x40000, v88
	global_atomic_add_f32 v86, v16, s[0:1]
	v_mul_f32_e32 v17, v17, v76
	v_add_u32_e32 v87, 0x42000, v88
	global_atomic_add_f32 v87, v17, s[0:1]
	v_mul_f32_e32 v18, v18, v76
	v_add_u32_e32 v84, 0x44000, v88
	global_atomic_add_f32 v84, v18, s[0:1]
	v_mul_f32_e32 v19, v19, v76
	v_add_u32_e32 v85, 0x46000, v88
	global_atomic_add_f32 v85, v19, s[0:1]
	v_mul_f32_e32 v20, v20, v77
	v_add_u32_e32 v86, 0x50000, v88
	global_atomic_add_f32 v86, v20, s[0:1]
	v_mul_f32_e32 v21, v21, v77
	v_add_u32_e32 v87, 0x52000, v88
	global_atomic_add_f32 v87, v21, s[0:1]
	v_mul_f32_e32 v22, v22, v77
	v_add_u32_e32 v84, 0x54000, v88
	global_atomic_add_f32 v84, v22, s[0:1]
	v_mul_f32_e32 v23, v23, v77
	v_add_u32_e32 v85, 0x56000, v88
	global_atomic_add_f32 v85, v23, s[0:1]
	v_mul_f32_e32 v24, v24, v78
	v_add_u32_e32 v86, 0x60000, v88
	global_atomic_add_f32 v86, v24, s[0:1]
	v_mul_f32_e32 v25, v25, v78
	v_add_u32_e32 v87, 0x62000, v88
	global_atomic_add_f32 v87, v25, s[0:1]
	v_mul_f32_e32 v26, v26, v78
	v_add_u32_e32 v84, 0x64000, v88
	global_atomic_add_f32 v84, v26, s[0:1]
	v_mul_f32_e32 v27, v27, v78
	v_add_u32_e32 v85, 0x66000, v88
	global_atomic_add_f32 v85, v27, s[0:1]
	v_mul_f32_e32 v28, v28, v79
	v_add_u32_e32 v86, 0x70000, v88
	global_atomic_add_f32 v86, v28, s[0:1]
	v_mul_f32_e32 v29, v29, v79
	v_add_u32_e32 v87, 0x72000, v88
	global_atomic_add_f32 v87, v29, s[0:1]
	v_mul_f32_e32 v30, v30, v79
	v_add_u32_e32 v84, 0x74000, v88
	global_atomic_add_f32 v84, v30, s[0:1]
	v_mul_f32_e32 v31, v31, v79
	v_add_u32_e32 v85, 0x76000, v88
	global_atomic_add_f32 v85, v31, s[0:1]
	s_and_b64 exec, s[8:9], vcc
	v_mul_f32_e32 v0, v0, v80
	v_add_u32_e32 v86, 0x40000, v88
	global_atomic_add_f32 v86, v0, s[0:1] offset:128
	v_mul_f32_e32 v1, v1, v80
	v_add_u32_e32 v87, 0x42000, v88
	global_atomic_add_f32 v87, v1, s[0:1] offset:128
	v_mul_f32_e32 v2, v2, v80
	v_add_u32_e32 v84, 0x44000, v88
	global_atomic_add_f32 v84, v2, s[0:1] offset:128
	v_mul_f32_e32 v3, v3, v80
	v_add_u32_e32 v85, 0x46000, v88
	global_atomic_add_f32 v85, v3, s[0:1] offset:128
	v_mul_f32_e32 v4, v4, v81
	v_add_u32_e32 v86, 0x50000, v88
	global_atomic_add_f32 v86, v4, s[0:1] offset:128
	v_mul_f32_e32 v5, v5, v81
	v_add_u32_e32 v87, 0x52000, v88
	global_atomic_add_f32 v87, v5, s[0:1] offset:128
	v_mul_f32_e32 v6, v6, v81
	v_add_u32_e32 v84, 0x54000, v88
	global_atomic_add_f32 v84, v6, s[0:1] offset:128
	v_mul_f32_e32 v7, v7, v81
	v_add_u32_e32 v85, 0x56000, v88
	global_atomic_add_f32 v85, v7, s[0:1] offset:128
	v_mul_f32_e32 v8, v8, v82
	v_add_u32_e32 v86, 0x60000, v88
	global_atomic_add_f32 v86, v8, s[0:1] offset:128
	v_mul_f32_e32 v9, v9, v82
	v_add_u32_e32 v87, 0x62000, v88
	global_atomic_add_f32 v87, v9, s[0:1] offset:128
	v_mul_f32_e32 v10, v10, v82
	v_add_u32_e32 v84, 0x64000, v88
	global_atomic_add_f32 v84, v10, s[0:1] offset:128
	v_mul_f32_e32 v11, v11, v82
	v_add_u32_e32 v85, 0x66000, v88
	global_atomic_add_f32 v85, v11, s[0:1] offset:128
	v_mul_f32_e32 v12, v12, v83
	v_add_u32_e32 v86, 0x70000, v88
	global_atomic_add_f32 v86, v12, s[0:1] offset:128
	v_mul_f32_e32 v13, v13, v83
	v_add_u32_e32 v87, 0x72000, v88
	global_atomic_add_f32 v87, v13, s[0:1] offset:128
	v_mul_f32_e32 v14, v14, v83
	v_add_u32_e32 v84, 0x74000, v88
	global_atomic_add_f32 v84, v14, s[0:1] offset:128
	v_mul_f32_e32 v15, v15, v83
	v_add_u32_e32 v85, 0x76000, v88
	global_atomic_add_f32 v85, v15, s[0:1] offset:128
	s_mov_b64 exec, s[8:9]

.LBB0_981:
	s_add_u32 m0, s100, 0x8000
	s_nop 0
	global_load_lds_dwordx4 v[108:109], off
	s_add_u32 m0, s100, 0x9000
	s_nop 0
	global_load_lds_dwordx4 v[128:129], off
	s_add_u32 m0, s100, 0xa000
	s_nop 0
	global_load_lds_dwordx4 v[130:131], off
	s_add_u32 m0, s100, 0xb000
	s_nop 0
	global_load_lds_dwordx4 v[132:133], off
	s_add_u32 m0, s100, 0xc000
	s_nop 0
	global_load_lds_dwordx4 v[134:135], off
	s_add_u32 m0, s100, 0xd000
	s_nop 0
	global_load_lds_dwordx4 v[144:145], off
	s_add_u32 m0, s100, 0xe000
	s_nop 0
	global_load_lds_dwordx4 v[146:147], off
	s_add_u32 m0, s100, 0xf000
	s_nop 0
	global_load_lds_dwordx4 v[148:149], off
	ds_read_b128 a[0:3], v104
	ds_read_b128 v[64:67], v107
	ds_read_b128 a[4:7], v104 offset:2048
	ds_read_b128 a[8:11], v104 offset:4096
	ds_read_b128 a[12:15], v104 offset:6144
	ds_read_b128 v[80:83], v107 offset:2048
	ds_read_b128 v[76:79], v107 offset:4096
	ds_read_b128 v[72:75], v107 offset:6144
	ds_read_b128 a[16:19], v105
	ds_read_b128 a[20:23], v105 offset:2048
	ds_read_b128 a[24:27], v105 offset:4096
	ds_read_b128 a[28:31], v105 offset:6144
	s_setprio 1
	s_waitcnt lgkmcnt(10)
	v_mfma_f32_16x16x32_bf16 v[0:3], a[0:3], v[64:67], v[0:3]
	s_waitcnt lgkmcnt(9)
	v_mfma_f32_16x16x32_bf16 v[16:19], a[4:7], v[64:67], v[16:19]
	s_waitcnt lgkmcnt(8)
	v_mfma_f32_16x16x32_bf16 v[32:35], a[8:11], v[64:67], v[32:35]
	s_waitcnt lgkmcnt(7)
	v_mfma_f32_16x16x32_bf16 v[48:51], a[12:15], v[64:67], v[48:51]
	ds_read_b128 v[64:67], v106
	s_waitcnt lgkmcnt(7)
	v_mfma_f32_16x16x32_bf16 v[4:7], a[0:3], v[80:83], v[4:7]
	v_lshl_add_u64 v[68:69], 8, 4, v[108:109]
	v_lshl_add_u64 v[70:71], 8, 4, v[128:129]
	v_lshl_add_u64 v[84:85], 8, 4, v[130:131]
	v_mfma_f32_16x16x32_bf16 v[20:23], a[4:7], v[80:83], v[20:23]
	v_lshl_add_u64 v[86:87], 8, 4, v[132:133]
	v_lshl_add_u64 v[92:93], 8, 4, v[134:135]
	v_lshl_add_u64 v[94:95], 8, 4, v[144:145]
	v_mfma_f32_16x16x32_bf16 v[36:39], a[8:11], v[80:83], v[36:39]
	v_lshl_add_u64 v[88:89], 8, 4, v[146:147]
	v_lshl_add_u64 v[90:91], 8, 4, v[148:149]
	v_mfma_f32_16x16x32_bf16 v[52:55], a[12:15], v[80:83], v[52:55]
	ds_read_b128 v[80:83], v106 offset:2048
	s_waitcnt lgkmcnt(7)
	v_mfma_f32_16x16x32_bf16 v[8:11], a[0:3], v[76:79], v[8:11]
	v_mfma_f32_16x16x32_bf16 v[24:27], a[4:7], v[76:79], v[24:27]
	v_mfma_f32_16x16x32_bf16 v[40:43], a[8:11], v[76:79], v[40:43]
	v_mfma_f32_16x16x32_bf16 v[56:59], a[12:15], v[76:79], v[56:59]
	ds_read_b128 v[76:79], v106 offset:4096
	s_waitcnt lgkmcnt(7)
	v_mfma_f32_16x16x32_bf16 v[12:15], a[0:3], v[72:75], v[12:15]
	v_mfma_f32_16x16x32_bf16 v[28:31], a[4:7], v[72:75], v[28:31]
	v_mfma_f32_16x16x32_bf16 v[44:47], a[8:11], v[72:75], v[44:47]
	v_mfma_f32_16x16x32_bf16 v[60:63], a[12:15], v[72:75], v[60:63]
	ds_read_b128 v[72:75], v106 offset:6144
	s_waitcnt lgkmcnt(3)
	v_mfma_f32_16x16x32_bf16 v[0:3], a[16:19], v[64:67], v[0:3]
	v_mfma_f32_16x16x32_bf16 v[16:19], a[20:23], v[64:67], v[16:19]
	v_mfma_f32_16x16x32_bf16 v[32:35], a[24:27], v[64:67], v[32:35]
	v_mfma_f32_16x16x32_bf16 v[48:51], a[28:31], v[64:67], v[48:51]
	s_waitcnt lgkmcnt(2)
	v_mfma_f32_16x16x32_bf16 v[4:7], a[16:19], v[80:83], v[4:7]
	v_mfma_f32_16x16x32_bf16 v[20:23], a[20:23], v[80:83], v[20:23]
	v_mfma_f32_16x16x32_bf16 v[36:39], a[24:27], v[80:83], v[36:39]
	v_mfma_f32_16x16x32_bf16 v[52:55], a[28:31], v[80:83], v[52:55]
	s_waitcnt lgkmcnt(1)
	v_mfma_f32_16x16x32_bf16 v[8:11], a[16:19], v[76:79], v[8:11]
	v_mfma_f32_16x16x32_bf16 v[24:27], a[20:23], v[76:79], v[24:27]
	v_mfma_f32_16x16x32_bf16 v[40:43], a[24:27], v[76:79], v[40:43]
	v_mfma_f32_16x16x32_bf16 v[56:59], a[28:31], v[76:79], v[56:59]
	s_waitcnt lgkmcnt(0)
	v_mfma_f32_16x16x32_bf16 v[12:15], a[16:19], v[72:75], v[12:15]
	v_mfma_f32_16x16x32_bf16 v[28:31], a[20:23], v[72:75], v[28:31]
	v_mfma_f32_16x16x32_bf16 v[44:47], a[24:27], v[72:75], v[44:47]
	v_mfma_f32_16x16x32_bf16 v[60:63], a[28:31], v[72:75], v[60:63]
	s_setprio 0
	s_waitcnt vmcnt(0) lgkmcnt(0)
	s_barrier
	s_add_u32 s30, s30, 0x100
	s_addc_u32 s31, s31, 0
	s_add_u32 m0, s100, 0x0
	s_nop 0
	global_load_lds_dwordx4 v[68:69], off
	s_add_u32 m0, s100, 0x1000
	s_nop 0
	global_load_lds_dwordx4 v[70:71], off
	s_add_u32 m0, s100, 0x2000
	s_nop 0
	global_load_lds_dwordx4 v[84:85], off
	s_add_u32 m0, s100, 0x3000
	s_nop 0
	global_load_lds_dwordx4 v[86:87], off
	s_add_u32 m0, s100, 0x4000
	s_nop 0
	global_load_lds_dwordx4 v[92:93], off
	s_add_u32 m0, s100, 0x5000
	s_nop 0
	global_load_lds_dwordx4 v[94:95], off
	s_add_u32 m0, s100, 0x6000
	s_nop 0
	global_load_lds_dwordx4 v[88:89], off
	s_add_u32 m0, s100, 0x7000
	s_nop 0
	global_load_lds_dwordx4 v[90:91], off
	ds_read_b128 a[0:3], v104 offset:32768
	ds_read_b128 v[64:67], v107 offset:32768
	ds_read_b128 a[4:7], v104 offset:34816
	ds_read_b128 a[8:11], v104 offset:36864
	ds_read_b128 a[12:15], v104 offset:38912
	ds_read_b128 v[80:83], v107 offset:34816
	ds_read_b128 v[76:79], v107 offset:36864
	ds_read_b128 v[72:75], v107 offset:38912
	ds_read_b128 a[16:19], v105 offset:32768
	ds_read_b128 a[20:23], v105 offset:34816
	ds_read_b128 a[24:27], v105 offset:36864
	ds_read_b128 a[28:31], v105 offset:38912
	s_setprio 1
	s_waitcnt lgkmcnt(10)
	v_mfma_f32_16x16x32_bf16 v[0:3], a[0:3], v[64:67], v[0:3]
	s_waitcnt lgkmcnt(9)
	v_mfma_f32_16x16x32_bf16 v[16:19], a[4:7], v[64:67], v[16:19]
	s_waitcnt lgkmcnt(8)
	v_mfma_f32_16x16x32_bf16 v[32:35], a[8:11], v[64:67], v[32:35]
	s_waitcnt lgkmcnt(7)
	v_mfma_f32_16x16x32_bf16 v[48:51], a[12:15], v[64:67], v[48:51]
	ds_read_b128 v[64:67], v106 offset:32768
	s_waitcnt lgkmcnt(7)
	v_mfma_f32_16x16x32_bf16 v[4:7], a[0:3], v[80:83], v[4:7]
	v_lshl_add_u64 v[120:121], v[96:97], 0, s[30:31]
	v_add_co_u32_e32 v108, vcc, s6, v120
	v_lshl_add_u64 v[122:123], v[98:99], 0, s[30:31]
	v_mfma_f32_16x16x32_bf16 v[20:23], a[4:7], v[80:83], v[20:23]
	s_nop 0
	v_addc_co_u32_e32 v109, vcc, 0, v121, vcc
	v_add_co_u32_e32 v128, vcc, s78, v120
	v_mfma_f32_16x16x32_bf16 v[36:39], a[8:11], v[80:83], v[36:39]
	s_nop 1
	v_addc_co_u32_e32 v129, vcc, 0, v121, vcc
	v_add_co_u32_e32 v130, vcc, s63, v120
	v_mfma_f32_16x16x32_bf16 v[52:55], a[12:15], v[80:83], v[52:55]
	v_addc_co_u32_e32 v131, vcc, 0, v121, vcc
	v_add_co_u32_e32 v132, vcc, s7, v120
	s_nop 1
	ds_read_b128 v[80:83], v106 offset:34816
	s_waitcnt lgkmcnt(7)
	v_mfma_f32_16x16x32_bf16 v[8:11], a[0:3], v[76:79], v[8:11]
	v_addc_co_u32_e32 v133, vcc, 0, v121, vcc
	v_add_co_u32_e32 v134, vcc, s79, v122
	v_addc_co_u32_e32 v135, vcc, 0, v123, vcc
	v_mfma_f32_16x16x32_bf16 v[24:27], a[4:7], v[76:79], v[24:27]
	v_add_co_u32_e32 v144, vcc, s82, v122
	s_nop 1
	v_addc_co_u32_e32 v145, vcc, 0, v123, vcc
	v_mfma_f32_16x16x32_bf16 v[40:43], a[8:11], v[76:79], v[40:43]
	v_add_co_u32_e32 v146, vcc, s2, v122
	v_addc_co_u32_e32 v147, vcc, 0, v123, vcc
	v_add_co_u32_e32 v148, vcc, s17, v122
	v_mfma_f32_16x16x32_bf16 v[56:59], a[12:15], v[76:79], v[56:59]
	s_nop 1
	v_addc_co_u32_e32 v149, vcc, 0, v123, vcc
	v_lshl_add_u64 v[108:109], 8, 4, v[108:109]
	ds_read_b128 v[76:79], v106 offset:36864
	s_waitcnt lgkmcnt(7)
	v_mfma_f32_16x16x32_bf16 v[12:15], a[0:3], v[72:75], v[12:15]
	v_lshl_add_u64 v[128:129], 8, 4, v[128:129]
	v_lshl_add_u64 v[130:131], 8, 4, v[130:131]
	v_lshl_add_u64 v[132:133], 8, 4, v[132:133]
	v_mfma_f32_16x16x32_bf16 v[28:31], a[4:7], v[72:75], v[28:31]
	v_lshl_add_u64 v[134:135], 8, 4, v[134:135]
	v_lshl_add_u64 v[144:145], 8, 4, v[144:145]
	v_lshl_add_u64 v[146:147], 8, 4, v[146:147]
	v_mfma_f32_16x16x32_bf16 v[44:47], a[8:11], v[72:75], v[44:47]
	v_lshl_add_u64 v[148:149], 8, 4, v[148:149]
	v_mfma_f32_16x16x32_bf16 v[60:63], a[12:15], v[72:75], v[60:63]
	ds_read_b128 v[72:75], v106 offset:38912
	s_waitcnt lgkmcnt(3)
	v_mfma_f32_16x16x32_bf16 v[0:3], a[16:19], v[64:67], v[0:3]
	v_mfma_f32_16x16x32_bf16 v[16:19], a[20:23], v[64:67], v[16:19]
	v_mfma_f32_16x16x32_bf16 v[32:35], a[24:27], v[64:67], v[32:35]
	v_mfma_f32_16x16x32_bf16 v[48:51], a[28:31], v[64:67], v[48:51]
	s_waitcnt lgkmcnt(2)
	v_mfma_f32_16x16x32_bf16 v[4:7], a[16:19], v[80:83], v[4:7]
	v_mfma_f32_16x16x32_bf16 v[20:23], a[20:23], v[80:83], v[20:23]
	v_mfma_f32_16x16x32_bf16 v[36:39], a[24:27], v[80:83], v[36:39]
	v_mfma_f32_16x16x32_bf16 v[52:55], a[28:31], v[80:83], v[52:55]
	s_waitcnt lgkmcnt(1)
	v_mfma_f32_16x16x32_bf16 v[8:11], a[16:19], v[76:79], v[8:11]
	v_mfma_f32_16x16x32_bf16 v[24:27], a[20:23], v[76:79], v[24:27]
	v_mfma_f32_16x16x32_bf16 v[40:43], a[24:27], v[76:79], v[40:43]
	v_mfma_f32_16x16x32_bf16 v[56:59], a[28:31], v[76:79], v[56:59]
	s_waitcnt lgkmcnt(0)
	v_mfma_f32_16x16x32_bf16 v[12:15], a[16:19], v[72:75], v[12:15]
	v_mfma_f32_16x16x32_bf16 v[28:31], a[20:23], v[72:75], v[28:31]
	v_mfma_f32_16x16x32_bf16 v[44:47], a[24:27], v[72:75], v[44:47]
	v_mfma_f32_16x16x32_bf16 v[60:63], a[28:31], v[72:75], v[60:63]
	s_setprio 0
	s_waitcnt vmcnt(0) lgkmcnt(0)
	s_barrier
	s_cmpk_eq_i32 s30, 0xf00
	s_cbranch_scc0 .LBB0_981
	v_lshl_add_u64 v[68:69], 8, 4, v[68:69]
	v_lshl_add_u64 v[70:71], 8, 4, v[70:71]
	v_lshl_add_u64 v[84:85], 8, 4, v[84:85]
	v_lshl_add_u64 v[86:87], 8, 4, v[86:87]
	v_lshl_add_u64 v[92:93], 8, 4, v[92:93]
	v_lshl_add_u64 v[94:95], 8, 4, v[94:95]
	v_lshl_add_u64 v[88:89], 8, 4, v[88:89]
	v_lshl_add_u64 v[90:91], 8, 4, v[90:91]
	s_add_u32 m0, s100, 0x8000
	s_nop 0
	global_load_lds_dwordx4 v[68:69], off
	s_add_u32 m0, s100, 0x9000
	s_nop 0
	global_load_lds_dwordx4 v[70:71], off
	s_add_u32 m0, s100, 0xa000
	s_nop 0
	global_load_lds_dwordx4 v[84:85], off
	s_add_u32 m0, s100, 0xb000
	s_nop 0
	global_load_lds_dwordx4 v[86:87], off
	s_add_u32 m0, s100, 0xc000
	s_nop 0
	global_load_lds_dwordx4 v[92:93], off
	s_add_u32 m0, s100, 0xd000
	s_nop 0
	global_load_lds_dwordx4 v[94:95], off
	s_add_u32 m0, s100, 0xe000
	s_nop 0
	global_load_lds_dwordx4 v[88:89], off
	s_add_u32 m0, s100, 0xf000
	s_nop 0
	global_load_lds_dwordx4 v[90:91], off
	ds_read_b128 a[0:3], v104
	ds_read_b128 v[64:67], v107
	ds_read_b128 a[4:7], v104 offset:2048
	ds_read_b128 a[8:11], v104 offset:4096
	ds_read_b128 a[12:15], v104 offset:6144
	ds_read_b128 v[80:83], v107 offset:2048
	ds_read_b128 v[76:79], v107 offset:4096
	ds_read_b128 v[72:75], v107 offset:6144
	ds_read_b128 a[16:19], v105
	ds_read_b128 a[20:23], v105 offset:2048
	ds_read_b128 a[24:27], v105 offset:4096
	ds_read_b128 a[28:31], v105 offset:6144
	s_setprio 1
	s_waitcnt lgkmcnt(10)
	v_mfma_f32_16x16x32_bf16 v[0:3], a[0:3], v[64:67], v[0:3]
	s_waitcnt lgkmcnt(9)
	v_mfma_f32_16x16x32_bf16 v[16:19], a[4:7], v[64:67], v[16:19]
	s_waitcnt lgkmcnt(8)
	v_mfma_f32_16x16x32_bf16 v[32:35], a[8:11], v[64:67], v[32:35]
	s_waitcnt lgkmcnt(7)
	v_mfma_f32_16x16x32_bf16 v[48:51], a[12:15], v[64:67], v[48:51]
	ds_read_b128 v[64:67], v106
	s_waitcnt lgkmcnt(7)
	v_mfma_f32_16x16x32_bf16 v[4:7], a[0:3], v[80:83], v[4:7]
	v_mfma_f32_16x16x32_bf16 v[20:23], a[4:7], v[80:83], v[20:23]
	v_mfma_f32_16x16x32_bf16 v[36:39], a[8:11], v[80:83], v[36:39]
	v_mfma_f32_16x16x32_bf16 v[52:55], a[12:15], v[80:83], v[52:55]
	ds_read_b128 v[80:83], v106 offset:2048
	s_waitcnt lgkmcnt(7)
	v_mfma_f32_16x16x32_bf16 v[8:11], a[0:3], v[76:79], v[8:11]
	v_mfma_f32_16x16x32_bf16 v[24:27], a[4:7], v[76:79], v[24:27]
	v_mfma_f32_16x16x32_bf16 v[40:43], a[8:11], v[76:79], v[40:43]
	v_mfma_f32_16x16x32_bf16 v[56:59], a[12:15], v[76:79], v[56:59]
	ds_read_b128 v[76:79], v106 offset:4096
	s_waitcnt lgkmcnt(7)
	v_mfma_f32_16x16x32_bf16 v[12:15], a[0:3], v[72:75], v[12:15]
	v_mfma_f32_16x16x32_bf16 v[28:31], a[4:7], v[72:75], v[28:31]
	v_mfma_f32_16x16x32_bf16 v[44:47], a[8:11], v[72:75], v[44:47]
	v_mfma_f32_16x16x32_bf16 v[60:63], a[12:15], v[72:75], v[60:63]
	ds_read_b128 v[72:75], v106 offset:6144
	s_waitcnt lgkmcnt(3)
	v_mfma_f32_16x16x32_bf16 v[0:3], a[16:19], v[64:67], v[0:3]
	v_mfma_f32_16x16x32_bf16 v[16:19], a[20:23], v[64:67], v[16:19]
	v_mfma_f32_16x16x32_bf16 v[32:35], a[24:27], v[64:67], v[32:35]
	v_mfma_f32_16x16x32_bf16 v[48:51], a[28:31], v[64:67], v[48:51]
	s_waitcnt lgkmcnt(2)
	v_mfma_f32_16x16x32_bf16 v[4:7], a[16:19], v[80:83], v[4:7]
	v_mfma_f32_16x16x32_bf16 v[20:23], a[20:23], v[80:83], v[20:23]
	v_mfma_f32_16x16x32_bf16 v[36:39], a[24:27], v[80:83], v[36:39]
	v_mfma_f32_16x16x32_bf16 v[52:55], a[28:31], v[80:83], v[52:55]
	s_waitcnt lgkmcnt(1)
	v_mfma_f32_16x16x32_bf16 v[8:11], a[16:19], v[76:79], v[8:11]
	v_mfma_f32_16x16x32_bf16 v[24:27], a[20:23], v[76:79], v[24:27]
	v_mfma_f32_16x16x32_bf16 v[40:43], a[24:27], v[76:79], v[40:43]
	v_mfma_f32_16x16x32_bf16 v[56:59], a[28:31], v[76:79], v[56:59]
	s_waitcnt lgkmcnt(0)
	v_mfma_f32_16x16x32_bf16 v[12:15], a[16:19], v[72:75], v[12:15]
	v_mfma_f32_16x16x32_bf16 v[28:31], a[20:23], v[72:75], v[28:31]
	v_mfma_f32_16x16x32_bf16 v[44:47], a[24:27], v[72:75], v[44:47]
	v_mfma_f32_16x16x32_bf16 v[60:63], a[28:31], v[72:75], v[60:63]
	s_setprio 0
	s_waitcnt vmcnt(0) lgkmcnt(0)
	s_barrier
	ds_read_b128 a[0:3], v104 offset:32768
	ds_read_b128 v[64:67], v107 offset:32768
	ds_read_b128 a[4:7], v104 offset:34816
	ds_read_b128 a[8:11], v104 offset:36864
	ds_read_b128 a[12:15], v104 offset:38912
	ds_read_b128 v[80:83], v107 offset:34816
	ds_read_b128 v[76:79], v107 offset:36864
	ds_read_b128 v[72:75], v107 offset:38912
	ds_read_b128 a[16:19], v105 offset:32768
	ds_read_b128 a[20:23], v105 offset:34816
	ds_read_b128 a[24:27], v105 offset:36864
	ds_read_b128 a[28:31], v105 offset:38912
	s_setprio 1
	s_waitcnt lgkmcnt(10)
	v_mfma_f32_16x16x32_bf16 v[0:3], a[0:3], v[64:67], v[0:3]
	s_waitcnt lgkmcnt(9)
	v_mfma_f32_16x16x32_bf16 v[16:19], a[4:7], v[64:67], v[16:19]
	s_waitcnt lgkmcnt(8)
	v_mfma_f32_16x16x32_bf16 v[32:35], a[8:11], v[64:67], v[32:35]
	s_waitcnt lgkmcnt(7)
	v_mfma_f32_16x16x32_bf16 v[48:51], a[12:15], v[64:67], v[48:51]
	ds_read_b128 v[64:67], v106 offset:32768
	s_waitcnt lgkmcnt(7)
	v_mfma_f32_16x16x32_bf16 v[4:7], a[0:3], v[80:83], v[4:7]
	v_mfma_f32_16x16x32_bf16 v[20:23], a[4:7], v[80:83], v[20:23]
	v_mfma_f32_16x16x32_bf16 v[36:39], a[8:11], v[80:83], v[36:39]
	v_mfma_f32_16x16x32_bf16 v[52:55], a[12:15], v[80:83], v[52:55]
	ds_read_b128 v[80:83], v106 offset:34816
	s_waitcnt lgkmcnt(7)
	v_mfma_f32_16x16x32_bf16 v[8:11], a[0:3], v[76:79], v[8:11]
	v_mfma_f32_16x16x32_bf16 v[24:27], a[4:7], v[76:79], v[24:27]
	v_mfma_f32_16x16x32_bf16 v[40:43], a[8:11], v[76:79], v[40:43]
	v_mfma_f32_16x16x32_bf16 v[56:59], a[12:15], v[76:79], v[56:59]
	ds_read_b128 v[76:79], v106 offset:36864
	s_waitcnt lgkmcnt(7)
	v_mfma_f32_16x16x32_bf16 v[12:15], a[0:3], v[72:75], v[12:15]
	v_mfma_f32_16x16x32_bf16 v[28:31], a[4:7], v[72:75], v[28:31]
	v_mfma_f32_16x16x32_bf16 v[44:47], a[8:11], v[72:75], v[44:47]
	v_mfma_f32_16x16x32_bf16 v[60:63], a[12:15], v[72:75], v[60:63]
	ds_read_b128 v[72:75], v106 offset:38912
	s_waitcnt lgkmcnt(3)
	v_mfma_f32_16x16x32_bf16 v[0:3], a[16:19], v[64:67], v[0:3]
	v_mfma_f32_16x16x32_bf16 v[16:19], a[20:23], v[64:67], v[16:19]
	v_mfma_f32_16x16x32_bf16 v[32:35], a[24:27], v[64:67], v[32:35]
	v_mfma_f32_16x16x32_bf16 v[48:51], a[28:31], v[64:67], v[48:51]
	s_waitcnt lgkmcnt(2)
	v_mfma_f32_16x16x32_bf16 v[4:7], a[16:19], v[80:83], v[4:7]
	v_mfma_f32_16x16x32_bf16 v[20:23], a[20:23], v[80:83], v[20:23]
	v_mfma_f32_16x16x32_bf16 v[36:39], a[24:27], v[80:83], v[36:39]
	v_mfma_f32_16x16x32_bf16 v[52:55], a[28:31], v[80:83], v[52:55]
	s_waitcnt lgkmcnt(1)
	v_mfma_f32_16x16x32_bf16 v[8:11], a[16:19], v[76:79], v[8:11]
	v_mfma_f32_16x16x32_bf16 v[24:27], a[20:23], v[76:79], v[24:27]
	v_mfma_f32_16x16x32_bf16 v[40:43], a[24:27], v[76:79], v[40:43]
	v_mfma_f32_16x16x32_bf16 v[56:59], a[28:31], v[76:79], v[56:59]
	s_waitcnt lgkmcnt(0)
	v_mfma_f32_16x16x32_bf16 v[12:15], a[16:19], v[72:75], v[12:15]
	v_mfma_f32_16x16x32_bf16 v[28:31], a[20:23], v[72:75], v[28:31]
	v_mfma_f32_16x16x32_bf16 v[44:47], a[24:27], v[72:75], v[44:47]
	v_mfma_f32_16x16x32_bf16 v[60:63], a[28:31], v[72:75], v[60:63]
	s_setprio 0
	v_readfirstlane_b32 s8, v113
	v_readfirstlane_b32 s4, v112
	s_lshl_b32 s8, s8, 6
	v_readlane_b32 s9, v219, 3
	s_waitcnt lgkmcnt(0)
	s_barrier
	s_add_i32 s8, s8, s9
	s_lshl_b32 s15, s4, 6
	v_readlane_b32 s4, v219, 2
	s_add_i32 s15, s15, s4
	v_or_b32_e32 v65, s8, v111
	s_movk_i32 s4, 0x800
	v_cmp_gt_i32_e64 s[38:39], s4, v65
	v_add_u32_e32 v64, 0x2800, v65
	v_lshl_or_b32 v66, v110, 2, s15
	v_or_b32_e32 v84, 32, v65
	s_movk_i32 s4, 0x800
	v_cmp_gt_i32_e32 vcc, s4, v84
	s_mov_b64 s[8:9], exec
	v_lshlrev_b32_e32 v90, 2, v64
	s_and_b64 exec, s[8:9], s[38:39]
	s_mov_b32 s4, s15
	s_add_i32 s22, s4, 0xffffe000
	s_lshr_b32 s22, s22, 3
	s_add_i32 s22, s22, 4
	s_ashr_i32 s23, s15, 11
	s_cmpk_lt_i32 s4, 0x2000
	s_cselect_b32 s22, s23, s22
	s_mul_i32 s22, s22, 0xc000
	v_add_u32_e32 v84, s22, v90
	global_load_dword v68, v84, s[26:27]
	s_add_i32 s4, s15, 8
	s_add_i32 s22, s4, 0xffffe000
	s_lshr_b32 s22, s22, 3
	s_add_i32 s22, s22, 4
	s_ashr_i32 s23, s15, 11
	s_cmpk_lt_i32 s4, 0x2000
	s_cselect_b32 s22, s23, s22
	s_mul_i32 s22, s22, 0xc000
	v_add_u32_e32 v85, s22, v90
	global_load_dword v69, v85, s[26:27]
	s_add_i32 s4, s15, 16
	s_add_i32 s22, s4, 0xffffe000
	s_lshr_b32 s22, s22, 3
	s_add_i32 s22, s22, 4
	s_ashr_i32 s23, s15, 11
	s_cmpk_lt_i32 s4, 0x2000
	s_cselect_b32 s22, s23, s22
	s_mul_i32 s22, s22, 0xc000
	v_add_u32_e32 v84, s22, v90
	global_load_dword v70, v84, s[26:27]
	s_add_i32 s4, s15, 24
	s_add_i32 s22, s4, 0xffffe000
	s_lshr_b32 s22, s22, 3
	s_add_i32 s22, s22, 4
	s_ashr_i32 s23, s15, 11
	s_cmpk_lt_i32 s4, 0x2000
	s_cselect_b32 s22, s23, s22
	s_mul_i32 s22, s22, 0xc000
	v_add_u32_e32 v85, s22, v90
	global_load_dword v71, v85, s[26:27]
	s_add_i32 s4, s15, 32
	s_add_i32 s22, s4, 0xffffe000
	s_lshr_b32 s22, s22, 3
	s_add_i32 s22, s22, 4
	s_ashr_i32 s23, s15, 11
	s_cmpk_lt_i32 s4, 0x2000
	s_cselect_b32 s22, s23, s22
	s_mul_i32 s22, s22, 0xc000
	v_add_u32_e32 v84, s22, v90
	global_load_dword v76, v84, s[26:27]
	s_add_i32 s4, s15, 40
	s_add_i32 s22, s4, 0xffffe000
	s_lshr_b32 s22, s22, 3
	s_add_i32 s22, s22, 4
	s_ashr_i32 s23, s15, 11
	s_cmpk_lt_i32 s4, 0x2000
	s_cselect_b32 s22, s23, s22
	s_mul_i32 s22, s22, 0xc000
	v_add_u32_e32 v85, s22, v90
	global_load_dword v77, v85, s[26:27]
	s_add_i32 s4, s15, 48
	s_add_i32 s22, s4, 0xffffe000
	s_lshr_b32 s22, s22, 3
	s_add_i32 s22, s22, 4
	s_ashr_i32 s23, s15, 11
	s_cmpk_lt_i32 s4, 0x2000
	s_cselect_b32 s22, s23, s22
	s_mul_i32 s22, s22, 0xc000
	v_add_u32_e32 v84, s22, v90
	global_load_dword v78, v84, s[26:27]
	s_add_i32 s4, s15, 56
	s_add_i32 s22, s4, 0xffffe000
	s_lshr_b32 s22, s22, 3
	s_add_i32 s22, s22, 4
	s_ashr_i32 s23, s15, 11
	s_cmpk_lt_i32 s4, 0x2000
	s_cselect_b32 s22, s23, s22
	s_mul_i32 s22, s22, 0xc000
	v_add_u32_e32 v85, s22, v90
	global_load_dword v79, v85, s[26:27]
	s_and_b64 exec, s[8:9], vcc
	s_mov_b32 s4, s15
	s_add_i32 s22, s4, 0xffffe000
	s_lshr_b32 s22, s22, 3
	s_add_i32 s22, s22, 4
	s_ashr_i32 s23, s15, 11
	s_cmpk_lt_i32 s4, 0x2000
	s_cselect_b32 s22, s23, s22
	s_mul_i32 s22, s22, 0xc000
	v_add_u32_e32 v84, s22, v90
	global_load_dword v72, v84, s[26:27] offset:128
	s_add_i32 s4, s15, 8
	s_add_i32 s22, s4, 0xffffe000
	s_lshr_b32 s22, s22, 3
	s_add_i32 s22, s22, 4
	s_ashr_i32 s23, s15, 11
	s_cmpk_lt_i32 s4, 0x2000
	s_cselect_b32 s22, s23, s22
	s_mul_i32 s22, s22, 0xc000
	v_add_u32_e32 v85, s22, v90
	global_load_dword v73, v85, s[26:27] offset:128
	s_add_i32 s4, s15, 16
	s_add_i32 s22, s4, 0xffffe000
	s_lshr_b32 s22, s22, 3
	s_add_i32 s22, s22, 4
	s_ashr_i32 s23, s15, 11
	s_cmpk_lt_i32 s4, 0x2000
	s_cselect_b32 s22, s23, s22
	s_mul_i32 s22, s22, 0xc000
	v_add_u32_e32 v84, s22, v90
	global_load_dword v74, v84, s[26:27] offset:128
	s_add_i32 s4, s15, 24
	s_add_i32 s22, s4, 0xffffe000
	s_lshr_b32 s22, s22, 3
	s_add_i32 s22, s22, 4
	s_ashr_i32 s23, s15, 11
	s_cmpk_lt_i32 s4, 0x2000
	s_cselect_b32 s22, s23, s22
	s_mul_i32 s22, s22, 0xc000
	v_add_u32_e32 v85, s22, v90
	global_load_dword v75, v85, s[26:27] offset:128
	s_add_i32 s4, s15, 32
	s_add_i32 s22, s4, 0xffffe000
	s_lshr_b32 s22, s22, 3
	s_add_i32 s22, s22, 4
	s_ashr_i32 s23, s15, 11
	s_cmpk_lt_i32 s4, 0x2000
	s_cselect_b32 s22, s23, s22
	s_mul_i32 s22, s22, 0xc000
	v_add_u32_e32 v84, s22, v90
	global_load_dword v80, v84, s[26:27] offset:128
	s_add_i32 s4, s15, 40
	s_add_i32 s22, s4, 0xffffe000
	s_lshr_b32 s22, s22, 3
	s_add_i32 s22, s22, 4
	s_ashr_i32 s23, s15, 11
	s_cmpk_lt_i32 s4, 0x2000
	s_cselect_b32 s22, s23, s22
	s_mul_i32 s22, s22, 0xc000
	v_add_u32_e32 v85, s22, v90
	global_load_dword v81, v85, s[26:27] offset:128
	s_add_i32 s4, s15, 48
	s_add_i32 s22, s4, 0xffffe000
	s_lshr_b32 s22, s22, 3
	s_add_i32 s22, s22, 4
	s_ashr_i32 s23, s15, 11
	s_cmpk_lt_i32 s4, 0x2000
	s_cselect_b32 s22, s23, s22
	s_mul_i32 s22, s22, 0xc000
	v_add_u32_e32 v84, s22, v90
	global_load_dword v82, v84, s[26:27] offset:128
	s_add_i32 s4, s15, 56
	s_add_i32 s22, s4, 0xffffe000
	s_lshr_b32 s22, s22, 3
	s_add_i32 s22, s22, 4
	s_ashr_i32 s23, s15, 11
	s_cmpk_lt_i32 s4, 0x2000
	s_cselect_b32 s22, s23, s22
	s_mul_i32 s22, s22, 0xc000
	v_add_u32_e32 v85, s22, v90
	global_load_dword v83, v85, s[26:27] offset:128
	s_mov_b64 exec, s[8:9]
	s_barrier
	v_and_b32_e32 v116, 15, v143
	v_bfe_u32 v117, v143, 4, 2
	v_xor_b32_e32 v117, v117, v116
	v_lshlrev_b32_e32 v117, 4, v117
	v_lshl_add_u32 v117, v116, 8, v117
	v_lshrrev_b32_e32 v116, 6, v143
	v_lshl_add_u32 v117, v116, 14, v117
	ds_write_b128 v117, v[0:3]
	ds_write_b128 v117, v[4:7] offset:4096
	ds_write_b128 v117, v[8:11] offset:8192
	ds_write_b128 v117, v[12:15] offset:12288
	v_xor_b32_e32 v106, 64, v117
	ds_write_b128 v106, v[16:19]
	ds_write_b128 v106, v[20:23] offset:4096
	ds_write_b128 v106, v[24:27] offset:8192
	ds_write_b128 v106, v[28:31] offset:12288
	v_xor_b32_e32 v106, 128, v117
	ds_write_b128 v106, v[32:35]
	ds_write_b128 v106, v[36:39] offset:4096
	ds_write_b128 v106, v[40:43] offset:8192
	ds_write_b128 v106, v[44:47] offset:12288
	v_xor_b32_e32 v106, 192, v117
	ds_write_b128 v106, v[48:51]
	ds_write_b128 v106, v[52:55] offset:4096
	ds_write_b128 v106, v[56:59] offset:8192
	ds_write_b128 v106, v[60:63] offset:12288
	v_and_b32_e32 v104, 31, v143
	v_bfe_u32 v105, v143, 5, 1
	v_and_b32_e32 v117, 15, v104
	v_xor_b32_e32 v105, v105, v117
	v_lshlrev_b32_e32 v105, 4, v105
	v_lshl_add_u32 v105, v104, 8, v105
	v_lshl_add_u32 v105, v116, 14, v105
	ds_read_b128 v[48:51], v105
	ds_read_b128 v[32:35], v105 offset:8192
	v_xor_b32_e32 v107, 32, v105
	ds_read_b128 v[52:55], v107
	ds_read_b128 v[36:39], v107 offset:8192
	v_xor_b32_e32 v107, 64, v105
	ds_read_b128 v[56:59], v107
	ds_read_b128 v[40:43], v107 offset:8192
	v_xor_b32_e32 v107, 96, v105
	ds_read_b128 v[60:63], v107
	ds_read_b128 v[44:47], v107 offset:8192
	v_xor_b32_e32 v107, 128, v105
	ds_read_b128 v[16:19], v107
	ds_read_b128 v[0:3], v107 offset:8192
	v_xor_b32_e32 v107, 160, v105
	ds_read_b128 v[20:23], v107
	ds_read_b128 v[4:7], v107 offset:8192
	v_xor_b32_e32 v107, 192, v105
	ds_read_b128 v[24:27], v107
	ds_read_b128 v[8:11], v107 offset:8192
	v_xor_b32_e32 v107, 224, v105
	ds_read_b128 v[28:31], v107
	ds_read_b128 v[12:15], v107 offset:8192
	s_waitcnt lgkmcnt(0)
	s_barrier
	v_lshl_add_u32 v88, v66, 11, v65
	v_lshlrev_b32_e32 v88, 2, v88
	s_waitcnt vmcnt(0)
	s_and_b64 exec, s[8:9], s[38:39]
	v_mul_f32_e32 v48, v48, v68
	global_atomic_add_f32 v88, v48, s[0:1]
	v_mul_f32_e32 v49, v49, v68
	v_add_u32_e32 v84, 0x2000, v88
	global_atomic_add_f32 v84, v49, s[0:1]
	v_mul_f32_e32 v50, v50, v68
	v_add_u32_e32 v85, 0x4000, v88
	global_atomic_add_f32 v85, v50, s[0:1]
	v_mul_f32_e32 v51, v51, v68
	v_add_u32_e32 v86, 0x6000, v88
	global_atomic_add_f32 v86, v51, s[0:1]
	v_mul_f32_e32 v52, v52, v69
	v_add_u32_e32 v87, 0x10000, v88
	global_atomic_add_f32 v87, v52, s[0:1]
	v_mul_f32_e32 v53, v53, v69
	v_add_u32_e32 v84, 0x12000, v88
	global_atomic_add_f32 v84, v53, s[0:1]
	v_mul_f32_e32 v54, v54, v69
	v_add_u32_e32 v85, 0x14000, v88
	global_atomic_add_f32 v85, v54, s[0:1]
	v_mul_f32_e32 v55, v55, v69
	v_add_u32_e32 v86, 0x16000, v88
	global_atomic_add_f32 v86, v55, s[0:1]
	v_mul_f32_e32 v56, v56, v70
	v_add_u32_e32 v87, 0x20000, v88
	global_atomic_add_f32 v87, v56, s[0:1]
	v_mul_f32_e32 v57, v57, v70
	v_add_u32_e32 v84, 0x22000, v88
	global_atomic_add_f32 v84, v57, s[0:1]
	v_mul_f32_e32 v58, v58, v70
	v_add_u32_e32 v85, 0x24000, v88
	global_atomic_add_f32 v85, v58, s[0:1]
	v_mul_f32_e32 v59, v59, v70
	v_add_u32_e32 v86, 0x26000, v88
	global_atomic_add_f32 v86, v59, s[0:1]
	v_mul_f32_e32 v60, v60, v71
	v_add_u32_e32 v87, 0x30000, v88
	global_atomic_add_f32 v87, v60, s[0:1]
	v_mul_f32_e32 v61, v61, v71
	v_add_u32_e32 v84, 0x32000, v88
	global_atomic_add_f32 v84, v61, s[0:1]
	v_mul_f32_e32 v62, v62, v71
	v_add_u32_e32 v85, 0x34000, v88
	global_atomic_add_f32 v85, v62, s[0:1]
	v_mul_f32_e32 v63, v63, v71
	v_add_u32_e32 v86, 0x36000, v88
	global_atomic_add_f32 v86, v63, s[0:1]
	s_and_b64 exec, s[8:9], vcc
	v_mul_f32_e32 v32, v32, v72
	global_atomic_add_f32 v88, v32, s[0:1] offset:128
	v_mul_f32_e32 v33, v33, v72
	v_add_u32_e32 v87, 0x2000, v88
	global_atomic_add_f32 v87, v33, s[0:1] offset:128
	v_mul_f32_e32 v34, v34, v72
	v_add_u32_e32 v84, 0x4000, v88
	global_atomic_add_f32 v84, v34, s[0:1] offset:128
	v_mul_f32_e32 v35, v35, v72
	v_add_u32_e32 v85, 0x6000, v88
	global_atomic_add_f32 v85, v35, s[0:1] offset:128
	v_mul_f32_e32 v36, v36, v73
	v_add_u32_e32 v86, 0x10000, v88
	global_atomic_add_f32 v86, v36, s[0:1] offset:128
	v_mul_f32_e32 v37, v37, v73
	v_add_u32_e32 v87, 0x12000, v88
	global_atomic_add_f32 v87, v37, s[0:1] offset:128
	v_mul_f32_e32 v38, v38, v73
	v_add_u32_e32 v84, 0x14000, v88
	global_atomic_add_f32 v84, v38, s[0:1] offset:128
	v_mul_f32_e32 v39, v39, v73
	v_add_u32_e32 v85, 0x16000, v88
	global_atomic_add_f32 v85, v39, s[0:1] offset:128
	v_mul_f32_e32 v40, v40, v74
	v_add_u32_e32 v86, 0x20000, v88
	global_atomic_add_f32 v86, v40, s[0:1] offset:128
	v_mul_f32_e32 v41, v41, v74
	v_add_u32_e32 v87, 0x22000, v88
	global_atomic_add_f32 v87, v41, s[0:1] offset:128
	v_mul_f32_e32 v42, v42, v74
	v_add_u32_e32 v84, 0x24000, v88
	global_atomic_add_f32 v84, v42, s[0:1] offset:128
	v_mul_f32_e32 v43, v43, v74
	v_add_u32_e32 v85, 0x26000, v88
	global_atomic_add_f32 v85, v43, s[0:1] offset:128
	v_mul_f32_e32 v44, v44, v75
	v_add_u32_e32 v86, 0x30000, v88
	global_atomic_add_f32 v86, v44, s[0:1] offset:128
	v_mul_f32_e32 v45, v45, v75
	v_add_u32_e32 v87, 0x32000, v88
	global_atomic_add_f32 v87, v45, s[0:1] offset:128
	v_mul_f32_e32 v46, v46, v75
	v_add_u32_e32 v84, 0x34000, v88
	global_atomic_add_f32 v84, v46, s[0:1] offset:128
	v_mul_f32_e32 v47, v47, v75
	v_add_u32_e32 v85, 0x36000, v88
	global_atomic_add_f32 v85, v47, s[0:1] offset:128
	s_and_b64 exec, s[8:9], s[38:39]
	v_mul_f32_e32 v16, v16, v76
	v_add_u32_e32 v86, 0x40000, v88
	global_atomic_add_f32 v86, v16, s[0:1]
	v_mul_f32_e32 v17, v17, v76
	v_add_u32_e32 v87, 0x42000, v88
	global_atomic_add_f32 v87, v17, s[0:1]
	v_mul_f32_e32 v18, v18, v76
	v_add_u32_e32 v84, 0x44000, v88
	global_atomic_add_f32 v84, v18, s[0:1]
	v_mul_f32_e32 v19, v19, v76
	v_add_u32_e32 v85, 0x46000, v88
	global_atomic_add_f32 v85, v19, s[0:1]
	v_mul_f32_e32 v20, v20, v77
	v_add_u32_e32 v86, 0x50000, v88
	global_atomic_add_f32 v86, v20, s[0:1]
	v_mul_f32_e32 v21, v21, v77
	v_add_u32_e32 v87, 0x52000, v88
	global_atomic_add_f32 v87, v21, s[0:1]
	v_mul_f32_e32 v22, v22, v77
	v_add_u32_e32 v84, 0x54000, v88
	global_atomic_add_f32 v84, v22, s[0:1]
	v_mul_f32_e32 v23, v23, v77
	v_add_u32_e32 v85, 0x56000, v88
	global_atomic_add_f32 v85, v23, s[0:1]
	v_mul_f32_e32 v24, v24, v78
	v_add_u32_e32 v86, 0x60000, v88
	global_atomic_add_f32 v86, v24, s[0:1]
	v_mul_f32_e32 v25, v25, v78
	v_add_u32_e32 v87, 0x62000, v88
	global_atomic_add_f32 v87, v25, s[0:1]
	v_mul_f32_e32 v26, v26, v78
	v_add_u32_e32 v84, 0x64000, v88
	global_atomic_add_f32 v84, v26, s[0:1]
	v_mul_f32_e32 v27, v27, v78
	v_add_u32_e32 v85, 0x66000, v88
	global_atomic_add_f32 v85, v27, s[0:1]
	v_mul_f32_e32 v28, v28, v79
	v_add_u32_e32 v86, 0x70000, v88
	global_atomic_add_f32 v86, v28, s[0:1]
	v_mul_f32_e32 v29, v29, v79
	v_add_u32_e32 v87, 0x72000, v88
	global_atomic_add_f32 v87, v29, s[0:1]
	v_mul_f32_e32 v30, v30, v79
	v_add_u32_e32 v84, 0x74000, v88
	global_atomic_add_f32 v84, v30, s[0:1]
	v_mul_f32_e32 v31, v31, v79
	v_add_u32_e32 v85, 0x76000, v88
	global_atomic_add_f32 v85, v31, s[0:1]
	s_and_b64 exec, s[8:9], vcc
	v_mul_f32_e32 v0, v0, v80
	v_add_u32_e32 v86, 0x40000, v88
	global_atomic_add_f32 v86, v0, s[0:1] offset:128
	v_mul_f32_e32 v1, v1, v80
	v_add_u32_e32 v87, 0x42000, v88
	global_atomic_add_f32 v87, v1, s[0:1] offset:128
	v_mul_f32_e32 v2, v2, v80
	v_add_u32_e32 v84, 0x44000, v88
	global_atomic_add_f32 v84, v2, s[0:1] offset:128
	v_mul_f32_e32 v3, v3, v80
	v_add_u32_e32 v85, 0x46000, v88
	global_atomic_add_f32 v85, v3, s[0:1] offset:128
	v_mul_f32_e32 v4, v4, v81
	v_add_u32_e32 v86, 0x50000, v88
	global_atomic_add_f32 v86, v4, s[0:1] offset:128
	v_mul_f32_e32 v5, v5, v81
	v_add_u32_e32 v87, 0x52000, v88
	global_atomic_add_f32 v87, v5, s[0:1] offset:128
	v_mul_f32_e32 v6, v6, v81
	v_add_u32_e32 v84, 0x54000, v88
	global_atomic_add_f32 v84, v6, s[0:1] offset:128
	v_mul_f32_e32 v7, v7, v81
	v_add_u32_e32 v85, 0x56000, v88
	global_atomic_add_f32 v85, v7, s[0:1] offset:128
	v_mul_f32_e32 v8, v8, v82
	v_add_u32_e32 v86, 0x60000, v88
	global_atomic_add_f32 v86, v8, s[0:1] offset:128
	v_mul_f32_e32 v9, v9, v82
	v_add_u32_e32 v87, 0x62000, v88
	global_atomic_add_f32 v87, v9, s[0:1] offset:128
	v_mul_f32_e32 v10, v10, v82
	v_add_u32_e32 v84, 0x64000, v88
	global_atomic_add_f32 v84, v10, s[0:1] offset:128
	v_mul_f32_e32 v11, v11, v82
	v_add_u32_e32 v85, 0x66000, v88
	global_atomic_add_f32 v85, v11, s[0:1] offset:128
	v_mul_f32_e32 v12, v12, v83
	v_add_u32_e32 v86, 0x70000, v88
	global_atomic_add_f32 v86, v12, s[0:1] offset:128
	v_mul_f32_e32 v13, v13, v83
	v_add_u32_e32 v87, 0x72000, v88
	global_atomic_add_f32 v87, v13, s[0:1] offset:128
	v_mul_f32_e32 v14, v14, v83
	v_add_u32_e32 v84, 0x74000, v88
	global_atomic_add_f32 v84, v14, s[0:1] offset:128
	v_mul_f32_e32 v15, v15, v83
	v_add_u32_e32 v85, 0x76000, v88
	global_atomic_add_f32 v85, v15, s[0:1] offset:128
	s_mov_b64 exec, s[8:9]

.LBB0_1021:
	s_andn2_b64 vcc, exec, s[26:27]
	s_cbranch_vccnz .LBB0_1099
	s_mov_b64 s[26:27], s[90:91]
	v_mov_b32_e32 v0, v143
	v_readlane_b32 s8, v220, 8
	v_readlane_b32 s9, v220, 9
	v_mov_b32_e32 v0, v143
	s_andn2_b64 vcc, exec, s[8:9]
	s_cbranch_vccnz .LBB0_1099
	s_load_dwordx2 s[8:9], s[26:27], 0x160
	v_lshrrev_b32_e32 v1, 4, v0
	v_xor_b32_e32 v2, v1, v0
	v_lshlrev_b32_e32 v2, 4, v2
	v_and_b32_e32 v2, 0x70, v2
	v_mov_b32_e32 v3, v140
	s_waitcnt lgkmcnt(0)
	v_lshl_add_u64 v[2:3], s[8:9], 0, v[2:3]
	s_mov_b64 s[22:23], 0xd70000
	s_waitcnt vmcnt(7)
	v_lshl_add_u64 v[96:97], v[2:3], 0, s[22:23]
	s_mov_b64 s[22:23], 0x2e380000
	v_bfe_u32 v4, v0, 5, 1
	s_waitcnt vmcnt(3)
	v_lshl_add_u64 v[98:99], v[2:3], 0, s[22:23]
	v_lshrrev_b32_e32 v2, 1, v0
	v_bfe_u32 v3, v0, 1, 3
	v_ashrrev_i32_e32 v106, 7, v0
	v_bfe_u32 v107, v0, 6, 1
	s_add_u32 s28, s8, 0x110000
	v_bitop3_b32 v2, v2, v4, 7 bitop3:0x6c
	v_bitop3_b32 v8, v4, v3, 2 bitop3:0x36
	v_bitop3_b32 v9, v4, v3, 4 bitop3:0x36
	v_bitop3_b32 v3, v4, v3, 6 bitop3:0x36
	v_and_b32_e32 v108, 31, v0
	v_ashrrev_i32_e32 v109, 3, v0
	s_addc_u32 s29, s9, 0
	s_waitcnt vmcnt(2)
	v_lshlrev_b32_e32 v110, 4, v0
	v_lshlrev_b32_e32 v2, 4, v2
	v_lshlrev_b32_e32 v5, 13, v106
	v_lshlrev_b32_e32 v7, 13, v107
	v_lshlrev_b32_e32 v8, 4, v8
	v_lshlrev_b32_e32 v9, 4, v9
	v_lshlrev_b32_e32 v3, 4, v3
	v_bitop3_b32 v0, v1, 7, v0 bitop3:0x48
	s_add_u32 s30, s8, 0x3170000
	v_lshlrev_b32_e32 v6, 7, v108
	v_or_b32_e32 v10, v2, v5
	v_or_b32_e32 v2, v2, v7
	v_or_b32_e32 v11, v8, v5
	v_or_b32_e32 v8, v8, v7
	v_or_b32_e32 v12, v9, v5
	v_or_b32_e32 v9, v9, v7
	v_or_b32_e32 v5, v3, v5
	v_or_b32_e32 v3, v3, v7
	v_lshlrev_b32_e32 v0, 4, v0
	v_mov_b32_e32 v1, v140
	s_addc_u32 s31, s9, 0
	v_lshlrev_b32_e32 v111, 13, v4
	v_lshl_add_u64 v[100:101], s[8:9], 0, v[0:1]
	s_waitcnt vmcnt(1)
	v_add_u32_e32 v112, v10, v6
	v_add_u32_e32 v113, v2, v6
	s_waitcnt vmcnt(0)
	v_add_u32_e32 v114, v11, v6
	v_add_u32_e32 v115, v8, v6
	v_add_u32_e32 v116, v12, v6
	v_add_u32_e32 v117, v9, v6
	v_add_u32_e32 v118, v5, v6
	v_add_u32_e32 v119, v3, v6
	v_readlane_b32 s42, v220, 2
	s_branch .LBB0_1026
.LBB0_1025:
	s_or_b64 exec, exec, s[34:35]
	s_add_i32 s42, s42, s3
	s_cmpk_gt_i32 s42, 0x47f
	s_cbranch_scc1 .LBB0_1099

.LBB0_1027:
	s_add_u32 m0, s100, 0x8000
	s_nop 0
	global_load_lds_dwordx4 v[132:133], off
	s_add_u32 m0, s100, 0x9000
	s_nop 0
	global_load_lds_dwordx4 v[134:135], off
	s_add_u32 m0, s100, 0xa000
	s_nop 0
	global_load_lds_dwordx4 v[144:145], off
	s_add_u32 m0, s100, 0xb000
	s_nop 0
	global_load_lds_dwordx4 v[146:147], off
	s_add_u32 m0, s100, 0xc000
	s_nop 0
	global_load_lds_dwordx4 v[148:149], off
	s_add_u32 m0, s100, 0xd000
	s_nop 0
	global_load_lds_dwordx4 v[150:151], off
	s_add_u32 m0, s100, 0xe000
	s_nop 0
	global_load_lds_dwordx4 v[152:153], off
	s_add_u32 m0, s100, 0xf000
	s_nop 0
	global_load_lds_dwordx4 v[154:155], off
	ds_read_b128 a[0:3], v112
	ds_read_b128 v[80:83], v113
	ds_read_b128 a[4:7], v112 offset:2048
	ds_read_b128 a[8:11], v112 offset:4096
	ds_read_b128 a[12:15], v112 offset:6144
	ds_read_b128 v[92:95], v113 offset:2048
	ds_read_b128 v[88:91], v113 offset:4096
	ds_read_b128 v[84:87], v113 offset:6144
	ds_read_b128 a[16:19], v114
	ds_read_b128 a[20:23], v114 offset:2048
	ds_read_b128 a[24:27], v114 offset:4096
	ds_read_b128 a[28:31], v114 offset:6144
	s_setprio 1
	s_waitcnt lgkmcnt(10)
	v_mfma_f32_16x16x32_bf16 v[0:3], a[0:3], v[80:83], v[0:3]
	s_waitcnt lgkmcnt(9)
	v_mfma_f32_16x16x32_bf16 v[16:19], a[4:7], v[80:83], v[16:19]
	s_waitcnt lgkmcnt(8)
	v_mfma_f32_16x16x32_bf16 v[32:35], a[8:11], v[80:83], v[32:35]
	s_waitcnt lgkmcnt(7)
	v_mfma_f32_16x16x32_bf16 v[48:51], a[12:15], v[80:83], v[48:51]
	ds_read_b128 v[80:83], v115
	s_waitcnt lgkmcnt(7)
	v_mfma_f32_16x16x32_bf16 v[4:7], a[0:3], v[92:95], v[4:7]
	v_lshl_add_u64 v[64:65], 8, 4, v[132:133]
	v_lshl_add_u64 v[66:67], 8, 4, v[134:135]
	v_lshl_add_u64 v[68:69], 8, 4, v[144:145]
	v_mfma_f32_16x16x32_bf16 v[20:23], a[4:7], v[92:95], v[20:23]
	v_lshl_add_u64 v[70:71], 8, 4, v[146:147]
	v_lshl_add_u64 v[76:77], 8, 4, v[148:149]
	v_lshl_add_u64 v[78:79], 8, 4, v[150:151]
	v_mfma_f32_16x16x32_bf16 v[36:39], a[8:11], v[92:95], v[36:39]
	v_lshl_add_u64 v[72:73], 8, 4, v[152:153]
	v_lshl_add_u64 v[74:75], 8, 4, v[154:155]
	v_mfma_f32_16x16x32_bf16 v[52:55], a[12:15], v[92:95], v[52:55]
	ds_read_b128 v[92:95], v115 offset:2048
	s_waitcnt lgkmcnt(7)
	v_mfma_f32_16x16x32_bf16 v[8:11], a[0:3], v[88:91], v[8:11]
	v_mfma_f32_16x16x32_bf16 v[24:27], a[4:7], v[88:91], v[24:27]
	v_mfma_f32_16x16x32_bf16 v[40:43], a[8:11], v[88:91], v[40:43]
	v_mfma_f32_16x16x32_bf16 v[56:59], a[12:15], v[88:91], v[56:59]
	ds_read_b128 v[88:91], v115 offset:4096
	s_waitcnt lgkmcnt(7)
	v_mfma_f32_16x16x32_bf16 v[12:15], a[0:3], v[84:87], v[12:15]
	v_mfma_f32_16x16x32_bf16 v[28:31], a[4:7], v[84:87], v[28:31]
	v_mfma_f32_16x16x32_bf16 v[44:47], a[8:11], v[84:87], v[44:47]
	v_mfma_f32_16x16x32_bf16 v[60:63], a[12:15], v[84:87], v[60:63]
	ds_read_b128 v[84:87], v115 offset:6144
	s_waitcnt lgkmcnt(3)
	v_mfma_f32_16x16x32_bf16 v[0:3], a[16:19], v[80:83], v[0:3]
	v_mfma_f32_16x16x32_bf16 v[16:19], a[20:23], v[80:83], v[16:19]
	v_mfma_f32_16x16x32_bf16 v[32:35], a[24:27], v[80:83], v[32:35]
	v_mfma_f32_16x16x32_bf16 v[48:51], a[28:31], v[80:83], v[48:51]
	s_waitcnt lgkmcnt(2)
	v_mfma_f32_16x16x32_bf16 v[4:7], a[16:19], v[92:95], v[4:7]
	v_mfma_f32_16x16x32_bf16 v[20:23], a[20:23], v[92:95], v[20:23]
	v_mfma_f32_16x16x32_bf16 v[36:39], a[24:27], v[92:95], v[36:39]
	v_mfma_f32_16x16x32_bf16 v[52:55], a[28:31], v[92:95], v[52:55]
	s_waitcnt lgkmcnt(1)
	v_mfma_f32_16x16x32_bf16 v[8:11], a[16:19], v[88:91], v[8:11]
	v_mfma_f32_16x16x32_bf16 v[24:27], a[20:23], v[88:91], v[24:27]
	v_mfma_f32_16x16x32_bf16 v[40:43], a[24:27], v[88:91], v[40:43]
	v_mfma_f32_16x16x32_bf16 v[56:59], a[28:31], v[88:91], v[56:59]
	s_waitcnt lgkmcnt(0)
	v_mfma_f32_16x16x32_bf16 v[12:15], a[16:19], v[84:87], v[12:15]
	v_mfma_f32_16x16x32_bf16 v[28:31], a[20:23], v[84:87], v[28:31]
	v_mfma_f32_16x16x32_bf16 v[44:47], a[24:27], v[84:87], v[44:47]
	v_mfma_f32_16x16x32_bf16 v[60:63], a[28:31], v[84:87], v[60:63]
	s_setprio 0
	s_waitcnt vmcnt(0) lgkmcnt(0)
	s_barrier
	s_add_u32 s34, s34, 0x100
	s_addc_u32 s35, s35, 0
	s_add_u32 m0, s100, 0x0
	s_nop 0
	global_load_lds_dwordx4 v[64:65], off
	s_add_u32 m0, s100, 0x1000
	s_nop 0
	global_load_lds_dwordx4 v[66:67], off
	s_add_u32 m0, s100, 0x2000
	s_nop 0
	global_load_lds_dwordx4 v[68:69], off
	s_add_u32 m0, s100, 0x3000
	s_nop 0
	global_load_lds_dwordx4 v[70:71], off
	s_add_u32 m0, s100, 0x4000
	s_nop 0
	global_load_lds_dwordx4 v[76:77], off
	s_add_u32 m0, s100, 0x5000
	s_nop 0
	global_load_lds_dwordx4 v[78:79], off
	s_add_u32 m0, s100, 0x6000
	s_nop 0
	global_load_lds_dwordx4 v[72:73], off
	s_add_u32 m0, s100, 0x7000
	s_nop 0
	global_load_lds_dwordx4 v[74:75], off
	ds_read_b128 a[0:3], v112 offset:32768
	ds_read_b128 v[80:83], v113 offset:32768
	ds_read_b128 a[4:7], v112 offset:34816
	ds_read_b128 a[8:11], v112 offset:36864
	ds_read_b128 a[12:15], v112 offset:38912
	ds_read_b128 v[92:95], v113 offset:34816
	ds_read_b128 v[88:91], v113 offset:36864
	ds_read_b128 v[84:87], v113 offset:38912
	ds_read_b128 a[16:19], v114 offset:32768
	ds_read_b128 a[20:23], v114 offset:34816
	ds_read_b128 a[24:27], v114 offset:36864
	ds_read_b128 a[28:31], v114 offset:38912
	s_setprio 1
	s_waitcnt lgkmcnt(10)
	v_mfma_f32_16x16x32_bf16 v[0:3], a[0:3], v[80:83], v[0:3]
	s_waitcnt lgkmcnt(9)
	v_mfma_f32_16x16x32_bf16 v[16:19], a[4:7], v[80:83], v[16:19]
	s_waitcnt lgkmcnt(8)
	v_mfma_f32_16x16x32_bf16 v[32:35], a[8:11], v[80:83], v[32:35]
	s_waitcnt lgkmcnt(7)
	v_mfma_f32_16x16x32_bf16 v[48:51], a[12:15], v[80:83], v[48:51]
	ds_read_b128 v[80:83], v115 offset:32768
	s_waitcnt lgkmcnt(7)
	v_mfma_f32_16x16x32_bf16 v[4:7], a[0:3], v[92:95], v[4:7]
	v_lshl_add_u64 v[124:125], v[104:105], 0, s[34:35]
	v_add_co_u32_e32 v132, vcc, s21, v124
	v_lshl_add_u64 v[126:127], v[102:103], 0, s[34:35]
	v_mfma_f32_16x16x32_bf16 v[20:23], a[4:7], v[92:95], v[20:23]
	s_nop 0
	v_addc_co_u32_e32 v133, vcc, 0, v125, vcc
	v_add_co_u32_e32 v134, vcc, s74, v124
	v_mfma_f32_16x16x32_bf16 v[36:39], a[8:11], v[92:95], v[36:39]
	s_mov_b32 s4, 0x2e380000
	s_nop 0
	v_addc_co_u32_e32 v135, vcc, 0, v125, vcc
	v_mfma_f32_16x16x32_bf16 v[52:55], a[12:15], v[92:95], v[52:55]
	v_add_co_u32_e32 v144, vcc, s75, v124
	v_addc_co_u32_e32 v145, vcc, 0, v125, vcc
	v_add_co_u32_e32 v146, vcc, s14, v124
	ds_read_b128 v[92:95], v115 offset:34816
	s_waitcnt lgkmcnt(7)
	v_mfma_f32_16x16x32_bf16 v[8:11], a[0:3], v[88:91], v[8:11]
	s_nop 1
	v_addc_co_u32_e32 v147, vcc, 0, v125, vcc
	v_add_co_u32_e32 v148, vcc, s4, v126
	v_mfma_f32_16x16x32_bf16 v[24:27], a[4:7], v[88:91], v[24:27]
	s_mov_b32 s4, 0x2e3a0000
	s_nop 0
	v_addc_co_u32_e32 v149, vcc, 0, v127, vcc
	v_mfma_f32_16x16x32_bf16 v[40:43], a[8:11], v[88:91], v[40:43]
	v_add_co_u32_e32 v150, vcc, s4, v126
	s_mov_b32 s4, 0x2e3c0000
	s_nop 0
	v_mfma_f32_16x16x32_bf16 v[56:59], a[12:15], v[88:91], v[56:59]
	v_addc_co_u32_e32 v151, vcc, 0, v127, vcc
	v_add_co_u32_e32 v152, vcc, s4, v126
	s_mov_b32 s4, 0x2e3e0000
	ds_read_b128 v[88:91], v115 offset:36864
	s_waitcnt lgkmcnt(7)
	v_mfma_f32_16x16x32_bf16 v[12:15], a[0:3], v[84:87], v[12:15]
	s_nop 0
	v_addc_co_u32_e32 v153, vcc, 0, v127, vcc
	v_add_co_u32_e32 v154, vcc, s4, v126
	v_mfma_f32_16x16x32_bf16 v[28:31], a[4:7], v[84:87], v[28:31]
	v_addc_co_u32_e32 v155, vcc, 0, v127, vcc
	v_lshl_add_u64 v[132:133], 8, 4, v[132:133]
	v_lshl_add_u64 v[134:135], 8, 4, v[134:135]
	v_mfma_f32_16x16x32_bf16 v[44:47], a[8:11], v[84:87], v[44:47]
	v_lshl_add_u64 v[144:145], 8, 4, v[144:145]
	v_lshl_add_u64 v[146:147], 8, 4, v[146:147]
	v_lshl_add_u64 v[148:149], 8, 4, v[148:149]
	v_mfma_f32_16x16x32_bf16 v[60:63], a[12:15], v[84:87], v[60:63]
	v_lshl_add_u64 v[150:151], 8, 4, v[150:151]
	v_lshl_add_u64 v[152:153], 8, 4, v[152:153]
	v_lshl_add_u64 v[154:155], 8, 4, v[154:155]
	ds_read_b128 v[84:87], v115 offset:38912
	s_waitcnt lgkmcnt(3)
	v_mfma_f32_16x16x32_bf16 v[0:3], a[16:19], v[80:83], v[0:3]
	v_mfma_f32_16x16x32_bf16 v[16:19], a[20:23], v[80:83], v[16:19]
	v_mfma_f32_16x16x32_bf16 v[32:35], a[24:27], v[80:83], v[32:35]
	v_mfma_f32_16x16x32_bf16 v[48:51], a[28:31], v[80:83], v[48:51]
	s_waitcnt lgkmcnt(2)
	v_mfma_f32_16x16x32_bf16 v[4:7], a[16:19], v[92:95], v[4:7]
	v_mfma_f32_16x16x32_bf16 v[20:23], a[20:23], v[92:95], v[20:23]
	v_mfma_f32_16x16x32_bf16 v[36:39], a[24:27], v[92:95], v[36:39]
	v_mfma_f32_16x16x32_bf16 v[52:55], a[28:31], v[92:95], v[52:55]
	s_waitcnt lgkmcnt(1)
	v_mfma_f32_16x16x32_bf16 v[8:11], a[16:19], v[88:91], v[8:11]
	v_mfma_f32_16x16x32_bf16 v[24:27], a[20:23], v[88:91], v[24:27]
	v_mfma_f32_16x16x32_bf16 v[40:43], a[24:27], v[88:91], v[40:43]
	v_mfma_f32_16x16x32_bf16 v[56:59], a[28:31], v[88:91], v[56:59]
	s_waitcnt lgkmcnt(0)
	v_mfma_f32_16x16x32_bf16 v[12:15], a[16:19], v[84:87], v[12:15]
	v_mfma_f32_16x16x32_bf16 v[28:31], a[20:23], v[84:87], v[28:31]
	v_mfma_f32_16x16x32_bf16 v[44:47], a[24:27], v[84:87], v[44:47]
	v_mfma_f32_16x16x32_bf16 v[60:63], a[28:31], v[84:87], v[60:63]
	s_setprio 0
	s_waitcnt vmcnt(0) lgkmcnt(0)
	s_barrier
	s_cmpk_eq_i32 s34, 0xf00
	s_cbranch_scc0 .LBB0_1027
	v_lshl_add_u64 v[64:65], 8, 4, v[64:65]
	v_lshl_add_u64 v[66:67], 8, 4, v[66:67]
	v_lshl_add_u64 v[68:69], 8, 4, v[68:69]
	v_lshl_add_u64 v[70:71], 8, 4, v[70:71]
	v_lshl_add_u64 v[76:77], 8, 4, v[76:77]
	v_lshl_add_u64 v[78:79], 8, 4, v[78:79]
	v_lshl_add_u64 v[72:73], 8, 4, v[72:73]
	v_lshl_add_u64 v[74:75], 8, 4, v[74:75]
	s_add_u32 m0, s100, 0x8000
	s_nop 0
	global_load_lds_dwordx4 v[64:65], off
	s_add_u32 m0, s100, 0x9000
	s_nop 0
	global_load_lds_dwordx4 v[66:67], off
	s_add_u32 m0, s100, 0xa000
	s_nop 0
	global_load_lds_dwordx4 v[68:69], off
	s_add_u32 m0, s100, 0xb000
	s_nop 0
	global_load_lds_dwordx4 v[70:71], off
	s_add_u32 m0, s100, 0xc000
	s_nop 0
	global_load_lds_dwordx4 v[76:77], off
	s_add_u32 m0, s100, 0xd000
	s_nop 0
	global_load_lds_dwordx4 v[78:79], off
	s_add_u32 m0, s100, 0xe000
	s_nop 0
	global_load_lds_dwordx4 v[72:73], off
	s_add_u32 m0, s100, 0xf000
	s_nop 0
	global_load_lds_dwordx4 v[74:75], off
	ds_read_b128 a[0:3], v112
	ds_read_b128 v[80:83], v113
	ds_read_b128 a[4:7], v112 offset:2048
	ds_read_b128 a[8:11], v112 offset:4096
	ds_read_b128 a[12:15], v112 offset:6144
	ds_read_b128 v[92:95], v113 offset:2048
	ds_read_b128 v[88:91], v113 offset:4096
	ds_read_b128 v[84:87], v113 offset:6144
	ds_read_b128 a[16:19], v114
	ds_read_b128 a[20:23], v114 offset:2048
	ds_read_b128 a[24:27], v114 offset:4096
	ds_read_b128 a[28:31], v114 offset:6144
	s_setprio 1
	s_waitcnt lgkmcnt(10)
	v_mfma_f32_16x16x32_bf16 v[0:3], a[0:3], v[80:83], v[0:3]
	s_waitcnt lgkmcnt(9)
	v_mfma_f32_16x16x32_bf16 v[16:19], a[4:7], v[80:83], v[16:19]
	s_waitcnt lgkmcnt(8)
	v_mfma_f32_16x16x32_bf16 v[32:35], a[8:11], v[80:83], v[32:35]
	s_waitcnt lgkmcnt(7)
	v_mfma_f32_16x16x32_bf16 v[48:51], a[12:15], v[80:83], v[48:51]
	ds_read_b128 v[80:83], v115
	s_waitcnt lgkmcnt(7)
	v_mfma_f32_16x16x32_bf16 v[4:7], a[0:3], v[92:95], v[4:7]
	v_mfma_f32_16x16x32_bf16 v[20:23], a[4:7], v[92:95], v[20:23]
	v_mfma_f32_16x16x32_bf16 v[36:39], a[8:11], v[92:95], v[36:39]
	v_mfma_f32_16x16x32_bf16 v[52:55], a[12:15], v[92:95], v[52:55]
	ds_read_b128 v[92:95], v115 offset:2048
	s_waitcnt lgkmcnt(7)
	v_mfma_f32_16x16x32_bf16 v[8:11], a[0:3], v[88:91], v[8:11]
	v_mfma_f32_16x16x32_bf16 v[24:27], a[4:7], v[88:91], v[24:27]
	v_mfma_f32_16x16x32_bf16 v[40:43], a[8:11], v[88:91], v[40:43]
	v_mfma_f32_16x16x32_bf16 v[56:59], a[12:15], v[88:91], v[56:59]
	ds_read_b128 v[88:91], v115 offset:4096
	s_waitcnt lgkmcnt(7)
	v_mfma_f32_16x16x32_bf16 v[12:15], a[0:3], v[84:87], v[12:15]
	v_mfma_f32_16x16x32_bf16 v[28:31], a[4:7], v[84:87], v[28:31]
	v_mfma_f32_16x16x32_bf16 v[44:47], a[8:11], v[84:87], v[44:47]
	v_mfma_f32_16x16x32_bf16 v[60:63], a[12:15], v[84:87], v[60:63]
	ds_read_b128 v[84:87], v115 offset:6144
	s_waitcnt lgkmcnt(3)
	v_mfma_f32_16x16x32_bf16 v[0:3], a[16:19], v[80:83], v[0:3]
	v_mfma_f32_16x16x32_bf16 v[16:19], a[20:23], v[80:83], v[16:19]
	v_mfma_f32_16x16x32_bf16 v[32:35], a[24:27], v[80:83], v[32:35]
	v_mfma_f32_16x16x32_bf16 v[48:51], a[28:31], v[80:83], v[48:51]
	s_waitcnt lgkmcnt(2)
	v_mfma_f32_16x16x32_bf16 v[4:7], a[16:19], v[92:95], v[4:7]
	v_mfma_f32_16x16x32_bf16 v[20:23], a[20:23], v[92:95], v[20:23]
	v_mfma_f32_16x16x32_bf16 v[36:39], a[24:27], v[92:95], v[36:39]
	v_mfma_f32_16x16x32_bf16 v[52:55], a[28:31], v[92:95], v[52:55]
	s_waitcnt lgkmcnt(1)
	v_mfma_f32_16x16x32_bf16 v[8:11], a[16:19], v[88:91], v[8:11]
	v_mfma_f32_16x16x32_bf16 v[24:27], a[20:23], v[88:91], v[24:27]
	v_mfma_f32_16x16x32_bf16 v[40:43], a[24:27], v[88:91], v[40:43]
	v_mfma_f32_16x16x32_bf16 v[56:59], a[28:31], v[88:91], v[56:59]
	s_waitcnt lgkmcnt(0)
	v_mfma_f32_16x16x32_bf16 v[12:15], a[16:19], v[84:87], v[12:15]
	v_mfma_f32_16x16x32_bf16 v[28:31], a[20:23], v[84:87], v[28:31]
	v_mfma_f32_16x16x32_bf16 v[44:47], a[24:27], v[84:87], v[44:47]
	v_mfma_f32_16x16x32_bf16 v[60:63], a[28:31], v[84:87], v[60:63]
	s_setprio 0
	s_waitcnt vmcnt(0) lgkmcnt(0)
	s_barrier
	ds_read_b128 a[0:3], v112 offset:32768
	ds_read_b128 v[80:83], v113 offset:32768
	ds_read_b128 a[4:7], v112 offset:34816
	ds_read_b128 a[8:11], v112 offset:36864
	ds_read_b128 a[12:15], v112 offset:38912
	ds_read_b128 v[92:95], v113 offset:34816
	ds_read_b128 v[88:91], v113 offset:36864
	ds_read_b128 v[84:87], v113 offset:38912
	ds_read_b128 a[16:19], v114 offset:32768
	ds_read_b128 a[20:23], v114 offset:34816
	ds_read_b128 a[24:27], v114 offset:36864
	ds_read_b128 a[28:31], v114 offset:38912
	s_setprio 1
	s_waitcnt lgkmcnt(10)
	v_mfma_f32_16x16x32_bf16 v[0:3], a[0:3], v[80:83], v[0:3]
	s_waitcnt lgkmcnt(9)
	v_mfma_f32_16x16x32_bf16 v[16:19], a[4:7], v[80:83], v[16:19]
	s_waitcnt lgkmcnt(8)
	v_mfma_f32_16x16x32_bf16 v[32:35], a[8:11], v[80:83], v[32:35]
	s_waitcnt lgkmcnt(7)
	v_mfma_f32_16x16x32_bf16 v[48:51], a[12:15], v[80:83], v[48:51]
	ds_read_b128 v[80:83], v115 offset:32768
	s_waitcnt lgkmcnt(7)
	v_mfma_f32_16x16x32_bf16 v[4:7], a[0:3], v[92:95], v[4:7]
	v_mfma_f32_16x16x32_bf16 v[20:23], a[4:7], v[92:95], v[20:23]
	v_mfma_f32_16x16x32_bf16 v[36:39], a[8:11], v[92:95], v[36:39]
	v_mfma_f32_16x16x32_bf16 v[52:55], a[12:15], v[92:95], v[52:55]
	ds_read_b128 v[92:95], v115 offset:34816
	s_waitcnt lgkmcnt(7)
	v_mfma_f32_16x16x32_bf16 v[8:11], a[0:3], v[88:91], v[8:11]
	v_mfma_f32_16x16x32_bf16 v[24:27], a[4:7], v[88:91], v[24:27]
	v_mfma_f32_16x16x32_bf16 v[40:43], a[8:11], v[88:91], v[40:43]
	v_mfma_f32_16x16x32_bf16 v[56:59], a[12:15], v[88:91], v[56:59]
	ds_read_b128 v[88:91], v115 offset:36864
	s_waitcnt lgkmcnt(7)
	v_mfma_f32_16x16x32_bf16 v[12:15], a[0:3], v[84:87], v[12:15]
	v_mfma_f32_16x16x32_bf16 v[28:31], a[4:7], v[84:87], v[28:31]
	v_mfma_f32_16x16x32_bf16 v[44:47], a[8:11], v[84:87], v[44:47]
	v_mfma_f32_16x16x32_bf16 v[60:63], a[12:15], v[84:87], v[60:63]
	ds_read_b128 v[84:87], v115 offset:38912
	s_waitcnt lgkmcnt(3)
	v_mfma_f32_16x16x32_bf16 v[0:3], a[16:19], v[80:83], v[0:3]
	v_mfma_f32_16x16x32_bf16 v[16:19], a[20:23], v[80:83], v[16:19]
	v_mfma_f32_16x16x32_bf16 v[32:35], a[24:27], v[80:83], v[32:35]
	v_mfma_f32_16x16x32_bf16 v[48:51], a[28:31], v[80:83], v[48:51]
	s_waitcnt lgkmcnt(2)
	v_mfma_f32_16x16x32_bf16 v[4:7], a[16:19], v[92:95], v[4:7]
	v_mfma_f32_16x16x32_bf16 v[20:23], a[20:23], v[92:95], v[20:23]
	v_mfma_f32_16x16x32_bf16 v[36:39], a[24:27], v[92:95], v[36:39]
	v_mfma_f32_16x16x32_bf16 v[52:55], a[28:31], v[92:95], v[52:55]
	s_waitcnt lgkmcnt(1)
	v_mfma_f32_16x16x32_bf16 v[8:11], a[16:19], v[88:91], v[8:11]
	v_mfma_f32_16x16x32_bf16 v[24:27], a[20:23], v[88:91], v[24:27]
	v_mfma_f32_16x16x32_bf16 v[40:43], a[24:27], v[88:91], v[40:43]
	v_mfma_f32_16x16x32_bf16 v[56:59], a[28:31], v[88:91], v[56:59]
	s_waitcnt lgkmcnt(0)
	v_mfma_f32_16x16x32_bf16 v[12:15], a[16:19], v[84:87], v[12:15]
	v_mfma_f32_16x16x32_bf16 v[28:31], a[20:23], v[84:87], v[28:31]
	v_mfma_f32_16x16x32_bf16 v[44:47], a[24:27], v[84:87], v[44:47]
	v_mfma_f32_16x16x32_bf16 v[60:63], a[28:31], v[84:87], v[60:63]
	s_setprio 0
	v_readfirstlane_b32 s15, v107
	v_readfirstlane_b32 s4, v106
	s_lshl_b32 s15, s15, 6
	s_waitcnt lgkmcnt(0)
	s_barrier
	s_add_i32 s15, s15, s9
	s_lshl_b32 s44, s4, 6
	s_add_i32 s44, s44, s8
	v_or_b32_e32 v65, s15, v108
	s_movk_i32 s4, 0x800
	s_ashr_i32 s43, s44, 11
	v_cmp_gt_i32_e64 s[40:41], s4, v65
	v_add_u32_e32 v64, 0x1000, v65
	s_load_dwordx2 s[8:9], s[26:27], 0x0
	s_load_dwordx2 s[36:37], s[26:27], 0x8
	s_waitcnt lgkmcnt(0)
	s_add_u32 s36, s36, 0xfc000000
	s_addc_u32 s37, s37, -1
	s_and_saveexec_b64 s[34:35], s[40:41]
	v_add_u32_e32 v90, v65, v111
	v_lshlrev_b32_e32 v90, 2, v90
	v_lshlrev_b32_e32 v91, 2, v64
	s_lshl_b32 s4, s44, 13
	v_add_u32_e32 v92, s4, v90
	s_mov_b32 s4, s44
	s_cmpk_lt_i32 s4, 0x2000
	s_cselect_b32 s100, s8, s36
	s_cselect_b32 s101, s9, s37
	s_mov_b32 s4, s44
	s_add_i32 s15, s4, 0xffffe000
	s_lshr_b32 s15, s15, 3
	s_add_i32 s15, s15, 4
	s_cmpk_lt_i32 s4, 0x2000
	s_cselect_b32 s15, s43, s15
	s_mul_i32 s15, s15, 0xc000
	v_add_u32_e32 v89, s15, v91
	global_load_dword v84, v89, s[28:29]
	s_add_i32 s4, s44, 8
	s_add_i32 s15, s4, 0xffffe000
	s_lshr_b32 s15, s15, 3
	s_add_i32 s15, s15, 4
	s_cmpk_lt_i32 s4, 0x2000
	s_cselect_b32 s15, s43, s15
	s_mul_i32 s15, s15, 0xc000
	v_add_u32_e32 v89, s15, v91
	global_load_dword v85, v89, s[28:29]
	s_add_i32 s4, s44, 16
	s_add_i32 s15, s4, 0xffffe000
	s_lshr_b32 s15, s15, 3
	s_add_i32 s15, s15, 4
	s_cmpk_lt_i32 s4, 0x2000
	s_cselect_b32 s15, s43, s15
	s_mul_i32 s15, s15, 0xc000
	v_add_u32_e32 v89, s15, v91
	global_load_dword v86, v89, s[28:29]
	s_add_i32 s4, s44, 24
	s_add_i32 s15, s4, 0xffffe000
	s_lshr_b32 s15, s15, 3
	s_add_i32 s15, s15, 4
	s_cmpk_lt_i32 s4, 0x2000
	s_cselect_b32 s15, s43, s15
	s_mul_i32 s15, s15, 0xc000
	v_add_u32_e32 v89, s15, v91
	global_load_dword v87, v89, s[28:29]
	global_load_dword v68, v92, s[100:101]
	v_add_u32_e32 v88, 0x2000, v92
	global_load_dword v69, v88, s[100:101]
	v_add_u32_e32 v88, 0x4000, v92
	global_load_dword v70, v88, s[100:101]
	v_add_u32_e32 v88, 0x6000, v92
	global_load_dword v71, v88, s[100:101]
	v_add_u32_e32 v88, 0x10000, v92
	global_load_dword v72, v88, s[100:101]
	v_add_u32_e32 v88, 0x12000, v92
	global_load_dword v73, v88, s[100:101]
	v_add_u32_e32 v88, 0x14000, v92
	global_load_dword v74, v88, s[100:101]
	v_add_u32_e32 v88, 0x16000, v92
	global_load_dword v75, v88, s[100:101]
	v_add_u32_e32 v88, 0x20000, v92
	global_load_dword v76, v88, s[100:101]
	v_add_u32_e32 v88, 0x22000, v92
	global_load_dword v77, v88, s[100:101]
	v_add_u32_e32 v88, 0x24000, v92
	global_load_dword v78, v88, s[100:101]
	v_add_u32_e32 v88, 0x26000, v92
	global_load_dword v79, v88, s[100:101]
	v_add_u32_e32 v88, 0x30000, v92
	global_load_dword v80, v88, s[100:101]
	v_add_u32_e32 v88, 0x32000, v92
	global_load_dword v81, v88, s[100:101]
	v_add_u32_e32 v88, 0x34000, v92
	global_load_dword v82, v88, s[100:101]
	v_add_u32_e32 v88, 0x36000, v92
	global_load_dword v83, v88, s[100:101]
	s_mov_b64 exec, s[34:35]
	s_barrier
	v_and_b32_e32 v120, 15, v143
	v_bfe_u32 v121, v143, 4, 2
	v_xor_b32_e32 v121, v121, v120
	v_lshlrev_b32_e32 v121, 4, v121
	v_lshl_add_u32 v121, v120, 8, v121
	v_lshrrev_b32_e32 v120, 6, v143
	v_lshl_add_u32 v121, v120, 14, v121
	ds_write_b128 v121, v[0:3]
	ds_write_b128 v121, v[4:7] offset:4096
	ds_write_b128 v121, v[8:11] offset:8192
	ds_write_b128 v121, v[12:15] offset:12288
	v_xor_b32_e32 v115, 64, v121
	ds_write_b128 v115, v[16:19]
	ds_write_b128 v115, v[20:23] offset:4096
	ds_write_b128 v115, v[24:27] offset:8192
	ds_write_b128 v115, v[28:31] offset:12288
	v_xor_b32_e32 v115, 128, v121
	ds_write_b128 v115, v[32:35]
	ds_write_b128 v115, v[36:39] offset:4096
	ds_write_b128 v115, v[40:43] offset:8192
	ds_write_b128 v115, v[44:47] offset:12288
	v_xor_b32_e32 v115, 192, v121
	ds_write_b128 v115, v[48:51]
	ds_write_b128 v115, v[52:55] offset:4096
	ds_write_b128 v115, v[56:59] offset:8192
	ds_write_b128 v115, v[60:63] offset:12288
	v_and_b32_e32 v112, 31, v143
	v_bfe_u32 v114, v143, 5, 1
	v_and_b32_e32 v121, 15, v112
	v_xor_b32_e32 v114, v114, v121
	v_lshlrev_b32_e32 v114, 4, v114
	v_lshl_add_u32 v114, v112, 8, v114
	v_lshl_add_u32 v114, v120, 14, v114
	ds_read_b128 v[48:51], v114
	ds_read_b128 v[32:35], v114 offset:8192
	v_xor_b32_e32 v113, 32, v114
	ds_read_b128 v[52:55], v113
	ds_read_b128 v[36:39], v113 offset:8192
	v_xor_b32_e32 v113, 64, v114
	ds_read_b128 v[56:59], v113
	ds_read_b128 v[40:43], v113 offset:8192
	v_xor_b32_e32 v113, 96, v114
	ds_read_b128 v[60:63], v113
	ds_read_b128 v[44:47], v113 offset:8192
	v_xor_b32_e32 v113, 128, v114
	ds_read_b128 v[16:19], v113
	ds_read_b128 v[0:3], v113 offset:8192
	v_xor_b32_e32 v113, 160, v114
	ds_read_b128 v[20:23], v113
	ds_read_b128 v[4:7], v113 offset:8192
	v_xor_b32_e32 v113, 192, v114
	ds_read_b128 v[24:27], v113
	ds_read_b128 v[8:11], v113 offset:8192
	v_xor_b32_e32 v113, 224, v114
	ds_read_b128 v[28:31], v113
	ds_read_b128 v[12:15], v113 offset:8192
	s_waitcnt lgkmcnt(0)
	s_barrier
	v_or_b32_e32 v89, 32, v65
	s_movk_i32 s4, 0x800
	v_cmp_gt_i32_e64 s[38:39], s4, v89
	s_mov_b64 s[34:35], exec
	s_and_b64 exec, s[34:35], s[40:41]
	s_waitcnt vmcnt(0)
	v_fma_f32 v48, v48, v84, v68
	v_fma_f32 v49, v49, v84, v69
	v_fma_f32 v50, v50, v84, v70
	v_fma_f32 v51, v51, v84, v71
	v_fma_f32 v52, v52, v85, v72
	v_fma_f32 v53, v53, v85, v73
	v_fma_f32 v54, v54, v85, v74
	v_fma_f32 v55, v55, v85, v75
	v_fma_f32 v56, v56, v86, v76
	v_fma_f32 v57, v57, v86, v77
	v_fma_f32 v58, v58, v86, v78
	v_fma_f32 v59, v59, v86, v79
	v_fma_f32 v60, v60, v87, v80
	v_fma_f32 v61, v61, v87, v81
	v_fma_f32 v62, v62, v87, v82
	v_fma_f32 v63, v63, v87, v83
	s_and_b64 exec, s[34:35], s[38:39]
	v_add_u32_e32 v90, v65, v111
	v_lshlrev_b32_e32 v90, 2, v90
	v_lshlrev_b32_e32 v91, 2, v64
	v_add_u32_e32 v90, 0x80, v90
	v_add_u32_e32 v91, 0x80, v91
	s_lshl_b32 s4, s44, 13
	v_add_u32_e32 v93, s4, v90
	s_mov_b32 s4, s44
	s_cmpk_lt_i32 s4, 0x2000
	s_cselect_b32 s100, s8, s36
	s_cselect_b32 s101, s9, s37
	s_mov_b32 s4, s44
	s_add_i32 s15, s4, 0xffffe000
	s_lshr_b32 s15, s15, 3
	s_add_i32 s15, s15, 4
	s_cmpk_lt_i32 s4, 0x2000
	s_cselect_b32 s15, s43, s15
	s_mul_i32 s15, s15, 0xc000
	v_add_u32_e32 v89, s15, v91
	global_load_dword v84, v89, s[28:29]
	s_add_i32 s4, s44, 8
	s_add_i32 s15, s4, 0xffffe000
	s_lshr_b32 s15, s15, 3
	s_add_i32 s15, s15, 4
	s_cmpk_lt_i32 s4, 0x2000
	s_cselect_b32 s15, s43, s15
	s_mul_i32 s15, s15, 0xc000
	v_add_u32_e32 v89, s15, v91
	global_load_dword v85, v89, s[28:29]
	s_add_i32 s4, s44, 16
	s_add_i32 s15, s4, 0xffffe000
	s_lshr_b32 s15, s15, 3
	s_add_i32 s15, s15, 4
	s_cmpk_lt_i32 s4, 0x2000
	s_cselect_b32 s15, s43, s15
	s_mul_i32 s15, s15, 0xc000
	v_add_u32_e32 v89, s15, v91
	global_load_dword v86, v89, s[28:29]
	s_add_i32 s4, s44, 24
	s_add_i32 s15, s4, 0xffffe000
	s_lshr_b32 s15, s15, 3
	s_add_i32 s15, s15, 4
	s_cmpk_lt_i32 s4, 0x2000
	s_cselect_b32 s15, s43, s15
	s_mul_i32 s15, s15, 0xc000
	v_add_u32_e32 v89, s15, v91
	global_load_dword v87, v89, s[28:29]
	global_load_dword v68, v93, s[100:101]
	v_add_u32_e32 v88, 0x2000, v93
	global_load_dword v69, v88, s[100:101]
	v_add_u32_e32 v88, 0x4000, v93
	global_load_dword v70, v88, s[100:101]
	v_add_u32_e32 v88, 0x6000, v93
	global_load_dword v71, v88, s[100:101]
	v_add_u32_e32 v88, 0x10000, v93
	global_load_dword v72, v88, s[100:101]
	v_add_u32_e32 v88, 0x12000, v93
	global_load_dword v73, v88, s[100:101]
	v_add_u32_e32 v88, 0x14000, v93
	global_load_dword v74, v88, s[100:101]
	v_add_u32_e32 v88, 0x16000, v93
	global_load_dword v75, v88, s[100:101]
	v_add_u32_e32 v88, 0x20000, v93
	global_load_dword v76, v88, s[100:101]
	v_add_u32_e32 v88, 0x22000, v93
	global_load_dword v77, v88, s[100:101]
	v_add_u32_e32 v88, 0x24000, v93
	global_load_dword v78, v88, s[100:101]
	v_add_u32_e32 v88, 0x26000, v93
	global_load_dword v79, v88, s[100:101]
	v_add_u32_e32 v88, 0x30000, v93
	global_load_dword v80, v88, s[100:101]
	v_add_u32_e32 v88, 0x32000, v93
	global_load_dword v81, v88, s[100:101]
	v_add_u32_e32 v88, 0x34000, v93
	global_load_dword v82, v88, s[100:101]
	v_add_u32_e32 v88, 0x36000, v93
	global_load_dword v83, v88, s[100:101]
	s_and_b64 exec, s[34:35], s[40:41]
	global_store_dword v92, v48, s[30:31]
	v_add_u32_e32 v88, 0x2000, v92
	global_store_dword v88, v49, s[30:31]
	v_add_u32_e32 v88, 0x4000, v92
	global_store_dword v88, v50, s[30:31]
	v_add_u32_e32 v88, 0x6000, v92
	global_store_dword v88, v51, s[30:31]
	v_add_u32_e32 v88, 0x10000, v92
	global_store_dword v88, v52, s[30:31]
	v_add_u32_e32 v88, 0x12000, v92
	global_store_dword v88, v53, s[30:31]
	v_add_u32_e32 v88, 0x14000, v92
	global_store_dword v88, v54, s[30:31]
	v_add_u32_e32 v88, 0x16000, v92
	global_store_dword v88, v55, s[30:31]
	v_add_u32_e32 v88, 0x20000, v92
	global_store_dword v88, v56, s[30:31]
	v_add_u32_e32 v88, 0x22000, v92
	global_store_dword v88, v57, s[30:31]
	v_add_u32_e32 v88, 0x24000, v92
	global_store_dword v88, v58, s[30:31]
	v_add_u32_e32 v88, 0x26000, v92
	global_store_dword v88, v59, s[30:31]
	v_add_u32_e32 v88, 0x30000, v92
	global_store_dword v88, v60, s[30:31]
	v_add_u32_e32 v88, 0x32000, v92
	global_store_dword v88, v61, s[30:31]
	v_add_u32_e32 v88, 0x34000, v92
	global_store_dword v88, v62, s[30:31]
	v_add_u32_e32 v88, 0x36000, v92
	global_store_dword v88, v63, s[30:31]
	s_and_b64 exec, s[34:35], s[38:39]
	s_waitcnt vmcnt(16)
	v_fma_f32 v32, v32, v84, v68
	v_fma_f32 v33, v33, v84, v69
	v_fma_f32 v34, v34, v84, v70
	v_fma_f32 v35, v35, v84, v71
	v_fma_f32 v36, v36, v85, v72
	v_fma_f32 v37, v37, v85, v73
	v_fma_f32 v38, v38, v85, v74
	v_fma_f32 v39, v39, v85, v75
	v_fma_f32 v40, v40, v86, v76
	v_fma_f32 v41, v41, v86, v77
	v_fma_f32 v42, v42, v86, v78
	v_fma_f32 v43, v43, v86, v79
	v_fma_f32 v44, v44, v87, v80
	v_fma_f32 v45, v45, v87, v81
	v_fma_f32 v46, v46, v87, v82
	v_fma_f32 v47, v47, v87, v83
	s_and_b64 exec, s[34:35], s[40:41]
	v_add_u32_e32 v90, v65, v111
	v_lshlrev_b32_e32 v90, 2, v90
	v_lshlrev_b32_e32 v91, 2, v64
	s_lshl_b32 s4, s44, 13
	v_add_u32_e32 v92, s4, v90
	s_add_i32 s4, s44, 32
	s_cmpk_lt_i32 s4, 0x2000
	s_cselect_b32 s100, s8, s36
	s_cselect_b32 s101, s9, s37
	s_add_i32 s4, s44, 32
	s_add_i32 s15, s4, 0xffffe000
	s_lshr_b32 s15, s15, 3
	s_add_i32 s15, s15, 4
	s_cmpk_lt_i32 s4, 0x2000
	s_cselect_b32 s15, s43, s15
	s_mul_i32 s15, s15, 0xc000
	v_add_u32_e32 v89, s15, v91
	global_load_dword v84, v89, s[28:29]
	s_add_i32 s4, s44, 40
	s_add_i32 s15, s4, 0xffffe000
	s_lshr_b32 s15, s15, 3
	s_add_i32 s15, s15, 4
	s_cmpk_lt_i32 s4, 0x2000
	s_cselect_b32 s15, s43, s15
	s_mul_i32 s15, s15, 0xc000
	v_add_u32_e32 v89, s15, v91
	global_load_dword v85, v89, s[28:29]
	s_add_i32 s4, s44, 48
	s_add_i32 s15, s4, 0xffffe000
	s_lshr_b32 s15, s15, 3
	s_add_i32 s15, s15, 4
	s_cmpk_lt_i32 s4, 0x2000
	s_cselect_b32 s15, s43, s15
	s_mul_i32 s15, s15, 0xc000
	v_add_u32_e32 v89, s15, v91
	global_load_dword v86, v89, s[28:29]
	s_add_i32 s4, s44, 56
	s_add_i32 s15, s4, 0xffffe000
	s_lshr_b32 s15, s15, 3
	s_add_i32 s15, s15, 4
	s_cmpk_lt_i32 s4, 0x2000
	s_cselect_b32 s15, s43, s15
	s_mul_i32 s15, s15, 0xc000
	v_add_u32_e32 v89, s15, v91
	global_load_dword v87, v89, s[28:29]
	v_add_u32_e32 v88, 0x40000, v92
	global_load_dword v68, v88, s[100:101]
	v_add_u32_e32 v88, 0x42000, v92
	global_load_dword v69, v88, s[100:101]
	v_add_u32_e32 v88, 0x44000, v92
	global_load_dword v70, v88, s[100:101]
	v_add_u32_e32 v88, 0x46000, v92
	global_load_dword v71, v88, s[100:101]
	v_add_u32_e32 v88, 0x50000, v92
	global_load_dword v72, v88, s[100:101]
	v_add_u32_e32 v88, 0x52000, v92
	global_load_dword v73, v88, s[100:101]
	v_add_u32_e32 v88, 0x54000, v92
	global_load_dword v74, v88, s[100:101]
	v_add_u32_e32 v88, 0x56000, v92
	global_load_dword v75, v88, s[100:101]
	v_add_u32_e32 v88, 0x60000, v92
	global_load_dword v76, v88, s[100:101]
	v_add_u32_e32 v88, 0x62000, v92
	global_load_dword v77, v88, s[100:101]
	v_add_u32_e32 v88, 0x64000, v92
	global_load_dword v78, v88, s[100:101]
	v_add_u32_e32 v88, 0x66000, v92
	global_load_dword v79, v88, s[100:101]
	v_add_u32_e32 v88, 0x70000, v92
	global_load_dword v80, v88, s[100:101]
	v_add_u32_e32 v88, 0x72000, v92
	global_load_dword v81, v88, s[100:101]
	v_add_u32_e32 v88, 0x74000, v92
	global_load_dword v82, v88, s[100:101]
	v_add_u32_e32 v88, 0x76000, v92
	global_load_dword v83, v88, s[100:101]
	s_and_b64 exec, s[34:35], s[38:39]
	global_store_dword v93, v32, s[30:31]
	v_add_u32_e32 v88, 0x2000, v93
	global_store_dword v88, v33, s[30:31]
	v_add_u32_e32 v88, 0x4000, v93
	global_store_dword v88, v34, s[30:31]
	v_add_u32_e32 v88, 0x6000, v93
	global_store_dword v88, v35, s[30:31]
	v_add_u32_e32 v88, 0x10000, v93
	global_store_dword v88, v36, s[30:31]
	v_add_u32_e32 v88, 0x12000, v93
	global_store_dword v88, v37, s[30:31]
	v_add_u32_e32 v88, 0x14000, v93
	global_store_dword v88, v38, s[30:31]
	v_add_u32_e32 v88, 0x16000, v93
	global_store_dword v88, v39, s[30:31]
	v_add_u32_e32 v88, 0x20000, v93
	global_store_dword v88, v40, s[30:31]
	v_add_u32_e32 v88, 0x22000, v93
	global_store_dword v88, v41, s[30:31]
	v_add_u32_e32 v88, 0x24000, v93
	global_store_dword v88, v42, s[30:31]
	v_add_u32_e32 v88, 0x26000, v93
	global_store_dword v88, v43, s[30:31]
	v_add_u32_e32 v88, 0x30000, v93
	global_store_dword v88, v44, s[30:31]
	v_add_u32_e32 v88, 0x32000, v93
	global_store_dword v88, v45, s[30:31]
	v_add_u32_e32 v88, 0x34000, v93
	global_store_dword v88, v46, s[30:31]
	v_add_u32_e32 v88, 0x36000, v93
	global_store_dword v88, v47, s[30:31]
	s_and_b64 exec, s[34:35], s[40:41]
	s_waitcnt vmcnt(16)
	v_fma_f32 v16, v16, v84, v68
	v_fma_f32 v17, v17, v84, v69
	v_fma_f32 v18, v18, v84, v70
	v_fma_f32 v19, v19, v84, v71
	v_fma_f32 v20, v20, v85, v72
	v_fma_f32 v21, v21, v85, v73
	v_fma_f32 v22, v22, v85, v74
	v_fma_f32 v23, v23, v85, v75
	v_fma_f32 v24, v24, v86, v76
	v_fma_f32 v25, v25, v86, v77
	v_fma_f32 v26, v26, v86, v78
	v_fma_f32 v27, v27, v86, v79
	v_fma_f32 v28, v28, v87, v80
	v_fma_f32 v29, v29, v87, v81
	v_fma_f32 v30, v30, v87, v82
	v_fma_f32 v31, v31, v87, v83
	s_and_b64 exec, s[34:35], s[38:39]
	v_add_u32_e32 v90, v65, v111
	v_lshlrev_b32_e32 v90, 2, v90
	v_lshlrev_b32_e32 v91, 2, v64
	v_add_u32_e32 v90, 0x80, v90
	v_add_u32_e32 v91, 0x80, v91
	s_lshl_b32 s4, s44, 13
	v_add_u32_e32 v93, s4, v90
	s_add_i32 s4, s44, 32
	s_cmpk_lt_i32 s4, 0x2000
	s_cselect_b32 s100, s8, s36
	s_cselect_b32 s101, s9, s37
	s_add_i32 s4, s44, 32
	s_add_i32 s15, s4, 0xffffe000
	s_lshr_b32 s15, s15, 3
	s_add_i32 s15, s15, 4
	s_cmpk_lt_i32 s4, 0x2000
	s_cselect_b32 s15, s43, s15
	s_mul_i32 s15, s15, 0xc000
	v_add_u32_e32 v89, s15, v91
	global_load_dword v84, v89, s[28:29]
	s_add_i32 s4, s44, 40
	s_add_i32 s15, s4, 0xffffe000
	s_lshr_b32 s15, s15, 3
	s_add_i32 s15, s15, 4
	s_cmpk_lt_i32 s4, 0x2000
	s_cselect_b32 s15, s43, s15
	s_mul_i32 s15, s15, 0xc000
	v_add_u32_e32 v89, s15, v91
	global_load_dword v85, v89, s[28:29]
	s_add_i32 s4, s44, 48
	s_add_i32 s15, s4, 0xffffe000
	s_lshr_b32 s15, s15, 3
	s_add_i32 s15, s15, 4
	s_cmpk_lt_i32 s4, 0x2000
	s_cselect_b32 s15, s43, s15
	s_mul_i32 s15, s15, 0xc000
	v_add_u32_e32 v89, s15, v91
	global_load_dword v86, v89, s[28:29]
	s_add_i32 s4, s44, 56
	s_add_i32 s15, s4, 0xffffe000
	s_lshr_b32 s15, s15, 3
	s_add_i32 s15, s15, 4
	s_cmpk_lt_i32 s4, 0x2000
	s_cselect_b32 s15, s43, s15
	s_mul_i32 s15, s15, 0xc000
	v_add_u32_e32 v89, s15, v91
	global_load_dword v87, v89, s[28:29]
	v_add_u32_e32 v88, 0x40000, v93
	global_load_dword v68, v88, s[100:101]
	v_add_u32_e32 v88, 0x42000, v93
	global_load_dword v69, v88, s[100:101]
	v_add_u32_e32 v88, 0x44000, v93
	global_load_dword v70, v88, s[100:101]
	v_add_u32_e32 v88, 0x46000, v93
	global_load_dword v71, v88, s[100:101]
	v_add_u32_e32 v88, 0x50000, v93
	global_load_dword v72, v88, s[100:101]
	v_add_u32_e32 v88, 0x52000, v93
	global_load_dword v73, v88, s[100:101]
	v_add_u32_e32 v88, 0x54000, v93
	global_load_dword v74, v88, s[100:101]
	v_add_u32_e32 v88, 0x56000, v93
	global_load_dword v75, v88, s[100:101]
	v_add_u32_e32 v88, 0x60000, v93
	global_load_dword v76, v88, s[100:101]
	v_add_u32_e32 v88, 0x62000, v93
	global_load_dword v77, v88, s[100:101]
	v_add_u32_e32 v88, 0x64000, v93
	global_load_dword v78, v88, s[100:101]
	v_add_u32_e32 v88, 0x66000, v93
	global_load_dword v79, v88, s[100:101]
	v_add_u32_e32 v88, 0x70000, v93
	global_load_dword v80, v88, s[100:101]
	v_add_u32_e32 v88, 0x72000, v93
	global_load_dword v81, v88, s[100:101]
	v_add_u32_e32 v88, 0x74000, v93
	global_load_dword v82, v88, s[100:101]
	v_add_u32_e32 v88, 0x76000, v93
	global_load_dword v83, v88, s[100:101]
	s_and_b64 exec, s[34:35], s[40:41]
	v_add_u32_e32 v88, 0x40000, v92
	global_store_dword v88, v16, s[30:31]
	v_add_u32_e32 v88, 0x42000, v92
	global_store_dword v88, v17, s[30:31]
	v_add_u32_e32 v88, 0x44000, v92
	global_store_dword v88, v18, s[30:31]
	v_add_u32_e32 v88, 0x46000, v92
	global_store_dword v88, v19, s[30:31]
	v_add_u32_e32 v88, 0x50000, v92
	global_store_dword v88, v20, s[30:31]
	v_add_u32_e32 v88, 0x52000, v92
	global_store_dword v88, v21, s[30:31]
	v_add_u32_e32 v88, 0x54000, v92
	global_store_dword v88, v22, s[30:31]
	v_add_u32_e32 v88, 0x56000, v92
	global_store_dword v88, v23, s[30:31]
	v_add_u32_e32 v88, 0x60000, v92
	global_store_dword v88, v24, s[30:31]
	v_add_u32_e32 v88, 0x62000, v92
	global_store_dword v88, v25, s[30:31]
	v_add_u32_e32 v88, 0x64000, v92
	global_store_dword v88, v26, s[30:31]
	v_add_u32_e32 v88, 0x66000, v92
	global_store_dword v88, v27, s[30:31]
	v_add_u32_e32 v88, 0x70000, v92
	global_store_dword v88, v28, s[30:31]
	v_add_u32_e32 v88, 0x72000, v92
	global_store_dword v88, v29, s[30:31]
	v_add_u32_e32 v88, 0x74000, v92
	global_store_dword v88, v30, s[30:31]
	v_add_u32_e32 v88, 0x76000, v92
	global_store_dword v88, v31, s[30:31]
	s_and_b64 exec, s[34:35], s[38:39]
	s_waitcnt vmcnt(16)
	v_fma_f32 v0, v0, v84, v68
	v_fma_f32 v1, v1, v84, v69
	v_fma_f32 v2, v2, v84, v70
	v_fma_f32 v3, v3, v84, v71
	v_fma_f32 v4, v4, v85, v72
	v_fma_f32 v5, v5, v85, v73
	v_fma_f32 v6, v6, v85, v74
	v_fma_f32 v7, v7, v85, v75
	v_fma_f32 v8, v8, v86, v76
	v_fma_f32 v9, v9, v86, v77
	v_fma_f32 v10, v10, v86, v78
	v_fma_f32 v11, v11, v86, v79
	v_fma_f32 v12, v12, v87, v80
	v_fma_f32 v13, v13, v87, v81
	v_fma_f32 v14, v14, v87, v82
	v_fma_f32 v15, v15, v87, v83
	v_add_u32_e32 v88, 0x40000, v93
	global_store_dword v88, v0, s[30:31]
	v_add_u32_e32 v88, 0x42000, v93
	global_store_dword v88, v1, s[30:31]
	v_add_u32_e32 v88, 0x44000, v93
	global_store_dword v88, v2, s[30:31]
	v_add_u32_e32 v88, 0x46000, v93
	global_store_dword v88, v3, s[30:31]
	v_add_u32_e32 v88, 0x50000, v93
	global_store_dword v88, v4, s[30:31]
	v_add_u32_e32 v88, 0x52000, v93
	global_store_dword v88, v5, s[30:31]
	v_add_u32_e32 v88, 0x54000, v93
	global_store_dword v88, v6, s[30:31]
	v_add_u32_e32 v88, 0x56000, v93
	global_store_dword v88, v7, s[30:31]
	v_add_u32_e32 v88, 0x60000, v93
	global_store_dword v88, v8, s[30:31]
	v_add_u32_e32 v88, 0x62000, v93
	global_store_dword v88, v9, s[30:31]
	v_add_u32_e32 v88, 0x64000, v93
	global_store_dword v88, v10, s[30:31]
	v_add_u32_e32 v88, 0x66000, v93
	global_store_dword v88, v11, s[30:31]
	v_add_u32_e32 v88, 0x70000, v93
	global_store_dword v88, v12, s[30:31]
	v_add_u32_e32 v88, 0x72000, v93
	global_store_dword v88, v13, s[30:31]
	v_add_u32_e32 v88, 0x74000, v93
	global_store_dword v88, v14, s[30:31]
	v_add_u32_e32 v88, 0x76000, v93
	global_store_dword v88, v15, s[30:31]
	s_branch .LBB0_1025
